# nt hint also on the once-read residual loads of the down-proj and gate epilogues (HB, PP), on top of P0/P3 streams and w_o-epilogue x loads
# speedup vs baseline: 1.0065x; 1.0065x over previous
; __device__ __forceinline__ u32x4 pack8(const f32x4 a, const f32x4 b) { u32x4 w; w.x = cvt_pk_bf16(a[0], a[1]); w.y = cvt_pk_bf16(a[2], a[3]); w.z = cvt_pk_bf16(b[0], b[1]); w.w = cvt_pk_bf16(b[2], b[3]); return w; }
;     __device__ __forceinline__ void operator()(const f32x4 (&acc)[2][2][4][2], const pg8::Unit& u, int wr, int wc, int fr, int fq) const {
;     ...
;         for (int ai = 0; ai < 2; ++ai) {
;             u32x4 hr[4][2]; float q1v[4];
; #pragma unroll
;             for (int m = 0; m < 4; ++m) { q1v[m] = rss1[row0 + ai * 128 + m * 16];
; #pragma unroll
;                 for (int bj = 0; bj < 2; ++bj) hr[m][bj] = *(const u32x4*)(HB + (size_t)(row0 + ai * 128 + m * 16) * DM + col0 + bj * 128); }
; #pragma unroll
;             for (int m = 0; m < 4; ++m) { const float iq = (127.f / QCLIP) * rsqrtf(q1v[m] * (1.f / DM) + EPS);
; #pragma unroll
;                 for (int bj = 0; bj < 2; ++bj) { float hv[8]; unpack8(hr[m][bj], hv); const size_t off = (size_t)(row0 + ai * 128 + m * 16) * DM + col0 + bj * 128;
;                     f32x4 h0 = acc[ai][bj][m][0], h1 = acc[ai][bj][m][1];
; #pragma unroll
;                     for (int e = 0; e < 4; ++e) { h0[e] += hv[e]; h1[e] += hv[4 + e]; }
;                     *(u32x4*)(HB + off) = pack8(h0, h1);
;                     f32x4 q0, q1;
; #pragma unroll
;                     for (int ee = 0; ee < 4; ++ee) { q0[ee] = fminf(fmaxf(rintf(h0[ee] * iq), -127.f), 127.f); q1[ee] = fminf(fmaxf(rintf(h1[ee] * iq), -127.f), 127.f); }
;                     *(u32x2*)(HQ + off) = pack8_i8(q0, q1); } }
.LBB0_1379:
	v_lshl_add_u32 v166, s1, 8, v1
	v_ashrrev_i32_e32 v167, 31, v166
	v_lshl_add_u64 v[168:169], v[166:167], 2, s[18:19]
	global_load_dword v187, v[168:169], off
	v_lshl_or_b32 v162, s4, 8, v181
	v_ashrrev_i32_e32 v163, 31, v162
	v_lshl_add_u64 v[164:165], v[162:163], 1, s[14:15]
	v_lshlrev_b64 v[130:131], 13, v[166:167]
	v_lshl_add_u64 v[200:201], v[164:165], 0, v[130:131]
	global_load_dwordx4 v[188:191], v[200:201], off nt
	v_or_b32_e32 v178, 16, v166
	v_ashrrev_i32_e32 v179, 31, v178
	v_lshl_add_u64 v[132:133], v[178:179], 2, s[18:19]
	global_load_dwordx4 v[192:195], v[200:201], off offset:256 nt
	global_load_dword v208, v[132:133], off
	v_or_b32_e32 v174, 32, v166
	v_or_b32_e32 v170, 48, v166
	v_ashrrev_i32_e32 v175, 31, v174
	v_ashrrev_i32_e32 v171, 31, v170
	v_lshlrev_b64 v[134:135], 13, v[178:179]
	v_lshlrev_b64 v[130:131], 12, v[166:167]
	v_lshl_add_u64 v[136:137], v[174:175], 2, s[18:19]
	v_lshlrev_b64 v[138:139], 13, v[174:175]
	v_lshlrev_b64 v[140:141], 13, v[170:171]
	v_lshl_add_u64 v[206:207], v[164:165], 0, v[134:135]
	v_lshl_add_u64 v[202:203], v[170:171], 2, s[18:19]
	v_lshl_add_u64 v[204:205], v[130:131], 0, v[162:163]
	v_lshl_add_u64 v[176:177], v[164:165], 0, v[138:139]
	v_lshl_add_u64 v[172:173], v[164:165], 0, v[140:141]
	global_load_dwordx4 v[196:199], v[206:207], off nt
	global_load_dwordx4 v[146:149], v[206:207], off offset:256 nt
	global_load_dword v209, v[136:137], off
	global_load_dwordx4 v[142:145], v[176:177], off nt
	global_load_dwordx4 v[138:141], v[176:177], off offset:256 nt
	global_load_dword v167, v[202:203], off
	s_nop 0
	global_load_dwordx4 v[134:137], v[172:173], off nt
	global_load_dwordx4 v[130:133], v[172:173], off offset:256 nt
	s_waitcnt vmcnt(0)
	v_fmamk_f32 v187, v187, 0x39800000, v185
	v_mul_f32_e32 v202, 0x4b800000, v187
	v_cmp_gt_f32_e32 vcc, s49, v187
	v_lshlrev_b32_e32 v203, 16, v188
	s_nop 0
	v_cndmask_b32_e32 v187, v187, v202, vcc
	v_rsq_f32_e32 v187, v187
	v_and_b32_e32 v188, 0xffff0000, v188
	v_lshlrev_b32_e32 v211, 16, v190
	v_lshlrev_b32_e32 v210, 16, v189
	v_and_b32_e32 v189, 0xffff0000, v189
	v_and_b32_e32 v190, 0xffff0000, v190
	v_lshlrev_b32_e32 v212, 16, v191
	v_and_b32_e32 v191, 0xffff0000, v191
	v_add_f32_e32 v126, v126, v203
	v_add_f32_e32 v202, v122, v211
	v_add_f32_e32 v127, v127, v188
	v_cvt_pk_bf16_f32 v122, v126, v127
	v_add_f32_e32 v188, v123, v190
	v_add_f32_e32 v128, v128, v210
	v_add_f32_e32 v190, v124, v212
	v_add_f32_e32 v129, v129, v189
	v_add_f32_e32 v189, v125, v191
	v_cvt_pk_bf16_f32 v123, v128, v129
	v_cvt_pk_bf16_f32 v124, v202, v188
	v_cvt_pk_bf16_f32 v125, v190, v189
	global_store_dwordx4 v[200:201], v[122:125], off
	s_nop 1
	v_mul_f32_e32 v122, 0x45800000, v187
	v_cndmask_b32_e32 v122, v187, v122, vcc
	v_mul_f32_e32 v187, 0x41e1c71c, v122
	v_mul_f32_e32 v124, v127, v187
	v_mul_f32_e32 v122, v126, v187
	v_mul_f32_e32 v126, v128, v187
	v_mul_f32_e32 v128, v129, v187
	v_rndne_f32_e32 v124, v124
	v_mul_f32_e32 v125, v188, v187
	v_rndne_f32_e32 v122, v122
	v_rndne_f32_e32 v126, v126
	v_rndne_f32_e32 v128, v128
	v_med3_f32 v124, v124, s50, v186
	v_mul_f32_e32 v123, v202, v187
	v_mul_f32_e32 v127, v190, v187
	v_mul_f32_e32 v129, v189, v187
	v_rndne_f32_e32 v125, v125
	v_med3_f32 v122, v122, s50, v186
	v_med3_f32 v126, v126, s50, v186
	v_med3_f32 v128, v128, s50, v186
	v_cvt_i32_f32_e32 v124, v124
	v_rndne_f32_e32 v123, v123
	v_rndne_f32_e32 v127, v127
	v_rndne_f32_e32 v129, v129
	v_med3_f32 v125, v125, s50, v186
	v_cvt_i32_f32_e32 v122, v122
	v_cvt_i32_f32_sdwa v126, v126 dst_sel:WORD_1 dst_unused:UNUSED_PAD src0_sel:DWORD
	v_cvt_i32_f32_e32 v128, v128
	v_med3_f32 v123, v123, s50, v186
	v_med3_f32 v127, v127, s50, v186
	v_med3_f32 v129, v129, s50, v186
	v_cvt_i32_f32_e32 v125, v125
	v_cvt_i32_f32_e32 v123, v123
	v_cvt_i32_f32_sdwa v127, v127 dst_sel:WORD_1 dst_unused:UNUSED_PAD src0_sel:DWORD
	v_cvt_i32_f32_e32 v129, v129
	v_lshlrev_b32_e32 v124, 8, v124
	v_and_b32_e32 v126, 0xff0000, v126
	v_perm_b32 v122, v128, v122, s51
	v_and_b32_e32 v124, 0xff00, v124
	v_or3_b32 v122, v122, v124, v126
	v_lshlrev_b32_e32 v124, 8, v125
	v_and_b32_e32 v124, 0xff00, v124
	v_and_b32_e32 v125, 0xff0000, v127
	v_perm_b32 v123, v129, v123, s51
	v_or3_b32 v123, v123, v124, v125
	v_lshl_add_u64 v[124:125], s[16:17], 0, v[204:205]
	global_store_dwordx2 v[124:125], v[122:123], off
	v_lshlrev_b32_e32 v122, 16, v192
	v_and_b32_e32 v123, 0xffff0000, v192
	v_lshlrev_b32_e32 v124, 16, v193
	v_and_b32_e32 v125, 0xffff0000, v193
	v_lshlrev_b32_e32 v126, 16, v194
	v_and_b32_e32 v127, 0xffff0000, v194
	v_lshlrev_b32_e32 v128, 16, v195
	v_or_b32_e32 v204, 0x80, v204
	v_and_b32_e32 v129, 0xffff0000, v195
	v_add_f32_e32 v122, v118, v122
	v_add_f32_e32 v126, v114, v126
	v_add_f32_e32 v123, v119, v123
	v_add_f32_e32 v127, v115, v127
	v_add_f32_e32 v120, v120, v124
	v_add_f32_e32 v124, v116, v128
	v_add_f32_e32 v121, v121, v125
	v_cvt_pk_bf16_f32 v114, v122, v123
	v_cvt_pk_bf16_f32 v115, v120, v121
	v_cvt_pk_bf16_f32 v116, v126, v127
	v_lshl_add_u64 v[118:119], v[204:205], 1, s[14:15]
	v_add_f32_e32 v125, v117, v129
	v_cvt_pk_bf16_f32 v117, v124, v125
	global_store_dwordx4 v[118:119], v[114:117], off
	v_mul_f32_e32 v118, v120, v187
	v_mul_f32_e32 v120, v121, v187
	v_mul_f32_e32 v116, v123, v187
	v_mul_f32_e32 v114, v122, v187
	v_rndne_f32_e32 v116, v116
	v_rndne_f32_e32 v114, v114
	v_med3_f32 v116, v116, s50, v186
	v_rndne_f32_e32 v118, v118
	v_rndne_f32_e32 v120, v120
	v_med3_f32 v114, v114, s50, v186
	v_med3_f32 v118, v118, s50, v186
	v_med3_f32 v120, v120, s50, v186
	v_cvt_i32_f32_e32 v116, v116
	v_cvt_i32_f32_e32 v114, v114
	v_cvt_i32_f32_sdwa v118, v118 dst_sel:WORD_1 dst_unused:UNUSED_PAD src0_sel:DWORD
; __device__ __forceinline__ u32x4 pack8(const f32x4 a, const f32x4 b) { u32x4 w; w.x = cvt_pk_bf16(a[0], a[1]); w.y = cvt_pk_bf16(a[2], a[3]); w.z = cvt_pk_bf16(b[0], b[1]); w.w = cvt_pk_bf16(b[2], b[3]); return w; }
;     __device__ __forceinline__ void operator()(const f32x4 (&acc)[2][2][4][2], const pg8::Unit& u, int wr, int wc, int fr, int fq) const {
;     ...
;             for (int m = 0; m < 4; ++m) { const float iq = (127.f / QCLIP) * rsqrtf(q1v[m] * (1.f / DM) + EPS);
; #pragma unroll
;                 for (int bj = 0; bj < 2; ++bj) { float hv[8]; unpack8(hr[m][bj], hv); const size_t off = (size_t)(row0 + ai * 128 + m * 16) * DM + col0 + bj * 128;
;                     f32x4 h0 = acc[ai][bj][m][0], h1 = acc[ai][bj][m][1];
; #pragma unroll
;                     for (int e = 0; e < 4; ++e) { h0[e] += hv[e]; h1[e] += hv[4 + e]; }
;                     *(u32x4*)(HB + off) = pack8(h0, h1);
;                     f32x4 q0, q1;
; #pragma unroll
;                     for (int ee = 0; ee < 4; ++ee) { q0[ee] = fminf(fmaxf(rintf(h0[ee] * iq), -127.f), 127.f); q1[ee] = fminf(fmaxf(rintf(h1[ee] * iq), -127.f), 127.f); }
;                     *(u32x2*)(HQ + off) = pack8_i8(q0, q1); } }
	v_cvt_i32_f32_e32 v120, v120
	v_mul_f32_e32 v115, v126, v187
	v_mul_f32_e32 v121, v125, v187
	v_rndne_f32_e32 v115, v115
	v_rndne_f32_e32 v121, v121
	v_lshlrev_b32_e32 v116, 8, v116
	v_med3_f32 v115, v115, s50, v186
	v_med3_f32 v121, v121, s50, v186
	v_and_b32_e32 v116, 0xff00, v116
	v_and_b32_e32 v118, 0xff0000, v118
	v_perm_b32 v114, v120, v114, s51
	v_or3_b32 v114, v114, v116, v118
	v_cvt_i32_f32_e32 v115, v115
	v_cvt_i32_f32_e32 v118, v121
	v_mul_f32_e32 v117, v127, v187
	v_rndne_f32_e32 v117, v117
	v_mul_f32_e32 v119, v124, v187
	v_med3_f32 v117, v117, s50, v186
	v_rndne_f32_e32 v119, v119
	v_med3_f32 v119, v119, s50, v186
	v_cvt_i32_f32_e32 v116, v117
	v_perm_b32 v115, v118, v115, s51
	v_fmamk_f32 v118, v208, 0x39800000, v185
	v_cvt_i32_f32_sdwa v117, v119 dst_sel:WORD_1 dst_unused:UNUSED_PAD src0_sel:DWORD
	v_mul_f32_e32 v119, 0x4b800000, v118
	v_cmp_gt_f32_e32 vcc, s49, v118
	v_lshlrev_b32_e32 v116, 8, v116
	v_and_b32_e32 v116, 0xff00, v116
	v_cndmask_b32_e32 v118, v118, v119, vcc
	v_rsq_f32_e32 v118, v118
	v_and_b32_e32 v117, 0xff0000, v117
	v_or3_b32 v115, v115, v116, v117
	v_lshl_add_u64 v[116:117], s[16:17], 0, v[204:205]
	global_store_dwordx2 v[116:117], v[114:115], off
	v_mul_f32_e32 v114, 0x45800000, v118
	v_cndmask_b32_e32 v114, v118, v114, vcc
	v_lshlrev_b32_e32 v117, 16, v196
	v_and_b32_e32 v118, 0xffff0000, v196
	v_lshlrev_b32_e32 v119, 16, v197
	v_and_b32_e32 v120, 0xffff0000, v197
	v_lshlrev_b32_e32 v121, 16, v198
	v_and_b32_e32 v122, 0xffff0000, v198
	v_lshlrev_b32_e32 v123, 16, v199
	v_mul_f32_e32 v116, 0x41e1c71c, v114
	v_and_b32_e32 v124, 0xffff0000, v199
	v_add_f32_e32 v110, v110, v117
	v_add_f32_e32 v117, v106, v121
	v_add_f32_e32 v111, v111, v118
	v_add_f32_e32 v118, v107, v122
	v_add_f32_e32 v112, v112, v119
	v_add_f32_e32 v119, v108, v123
	v_add_f32_e32 v113, v113, v120
	v_cvt_pk_bf16_f32 v106, v110, v111
	v_cvt_pk_bf16_f32 v107, v112, v113
	v_cvt_pk_bf16_f32 v108, v117, v118
	v_add_f32_e32 v120, v109, v124
	v_cvt_pk_bf16_f32 v109, v119, v120
	global_store_dwordx4 v[206:207], v[106:109], off
	v_lshlrev_b64 v[114:115], 12, v[178:179]
	v_lshl_add_u64 v[114:115], v[114:115], 0, v[162:163]
	v_mul_f32_e32 v108, v111, v116
	v_mul_f32_e32 v106, v110, v116
	v_rndne_f32_e32 v108, v108
	v_mul_f32_e32 v110, v112, v116
	v_mul_f32_e32 v112, v113, v116
	v_rndne_f32_e32 v106, v106
	v_med3_f32 v108, v108, s50, v186
	v_rndne_f32_e32 v110, v110
	v_rndne_f32_e32 v112, v112
	v_med3_f32 v106, v106, s50, v186
	v_med3_f32 v110, v110, s50, v186
	v_med3_f32 v112, v112, s50, v186
	v_cvt_i32_f32_e32 v108, v108
	v_cvt_i32_f32_e32 v106, v106
	v_cvt_i32_f32_sdwa v110, v110 dst_sel:WORD_1 dst_unused:UNUSED_PAD src0_sel:DWORD
	v_cvt_i32_f32_e32 v112, v112
	v_mul_f32_e32 v109, v118, v116
	v_mul_f32_e32 v107, v117, v116
	v_rndne_f32_e32 v109, v109
	v_mul_f32_e32 v111, v119, v116
	v_mul_f32_e32 v113, v120, v116
	v_lshlrev_b32_e32 v108, 8, v108
	v_rndne_f32_e32 v107, v107
	v_med3_f32 v109, v109, s50, v186
	v_rndne_f32_e32 v111, v111
	v_rndne_f32_e32 v113, v113
	v_and_b32_e32 v108, 0xff00, v108
	v_and_b32_e32 v110, 0xff0000, v110
	v_perm_b32 v106, v112, v106, s51
	v_med3_f32 v107, v107, s50, v186
	v_med3_f32 v111, v111, s50, v186
	v_med3_f32 v113, v113, s50, v186
	v_or3_b32 v106, v106, v108, v110
	v_cvt_i32_f32_e32 v108, v109
	v_cvt_i32_f32_e32 v107, v107
	v_cvt_i32_f32_sdwa v109, v111 dst_sel:WORD_1 dst_unused:UNUSED_PAD src0_sel:DWORD
	v_cvt_i32_f32_e32 v110, v113
	v_lshlrev_b32_e32 v108, 8, v108
	v_and_b32_e32 v108, 0xff00, v108
	v_and_b32_e32 v109, 0xff0000, v109
	v_perm_b32 v107, v110, v107, s51
	v_or3_b32 v107, v107, v108, v109
	v_lshl_add_u64 v[108:109], s[16:17], 0, v[114:115]
	global_store_dwordx2 v[108:109], v[106:107], off
	v_lshlrev_b32_e32 v106, 16, v146
	v_and_b32_e32 v107, 0xffff0000, v146
	v_lshlrev_b32_e32 v108, 16, v147
	v_and_b32_e32 v109, 0xffff0000, v147
	v_lshlrev_b32_e32 v110, 16, v148
	v_and_b32_e32 v111, 0xffff0000, v148
	v_lshlrev_b32_e32 v112, 16, v149
	v_or_b32_e32 v114, 0x80, v114
	v_and_b32_e32 v113, 0xffff0000, v149
	v_add_f32_e32 v106, v102, v106
	v_add_f32_e32 v110, v98, v110
	v_add_f32_e32 v107, v103, v107
	v_add_f32_e32 v111, v99, v111
	v_add_f32_e32 v104, v104, v108
	v_add_f32_e32 v108, v100, v112
	v_add_f32_e32 v105, v105, v109
	v_cvt_pk_bf16_f32 v98, v106, v107
	v_cvt_pk_bf16_f32 v99, v104, v105
	v_cvt_pk_bf16_f32 v100, v110, v111
	v_lshl_add_u64 v[102:103], v[114:115], 1, s[14:15]
	v_add_f32_e32 v109, v101, v113
	v_cvt_pk_bf16_f32 v101, v108, v109
	global_store_dwordx4 v[102:103], v[98:101], off
	v_mul_f32_e32 v102, v104, v116
	v_mul_f32_e32 v104, v105, v116
	v_mul_f32_e32 v100, v107, v116
	v_mul_f32_e32 v98, v106, v116
	v_rndne_f32_e32 v100, v100
	v_rndne_f32_e32 v98, v98
	v_med3_f32 v100, v100, s50, v186
	v_rndne_f32_e32 v102, v102
	v_rndne_f32_e32 v104, v104
	v_med3_f32 v98, v98, s50, v186
	v_med3_f32 v102, v102, s50, v186
	v_med3_f32 v104, v104, s50, v186
	v_cvt_i32_f32_e32 v100, v100
	v_cvt_i32_f32_e32 v98, v98
	v_cvt_i32_f32_sdwa v102, v102 dst_sel:WORD_1 dst_unused:UNUSED_PAD src0_sel:DWORD
	v_cvt_i32_f32_e32 v104, v104
	v_mul_f32_e32 v99, v110, v116
	v_mul_f32_e32 v105, v109, v116
	v_rndne_f32_e32 v99, v99
	v_rndne_f32_e32 v105, v105
	v_lshlrev_b32_e32 v100, 8, v100
	v_med3_f32 v99, v99, s50, v186
	v_med3_f32 v105, v105, s50, v186
	v_and_b32_e32 v100, 0xff00, v100
	v_and_b32_e32 v102, 0xff0000, v102
	v_perm_b32 v98, v104, v98, s51
	v_or3_b32 v98, v98, v100, v102
	v_cvt_i32_f32_e32 v99, v99
	v_cvt_i32_f32_e32 v102, v105
	v_mul_f32_e32 v101, v111, v116
	v_rndne_f32_e32 v101, v101
	v_mul_f32_e32 v103, v108, v116
	v_med3_f32 v101, v101, s50, v186
	v_rndne_f32_e32 v103, v103
	v_med3_f32 v103, v103, s50, v186
; __device__ __forceinline__ u32x4 pack8(const f32x4 a, const f32x4 b) { u32x4 w; w.x = cvt_pk_bf16(a[0], a[1]); w.y = cvt_pk_bf16(a[2], a[3]); w.z = cvt_pk_bf16(b[0], b[1]); w.w = cvt_pk_bf16(b[2], b[3]); return w; }
;     __device__ __forceinline__ void operator()(const f32x4 (&acc)[2][2][4][2], const pg8::Unit& u, int wr, int wc, int fr, int fq) const {
;     ...
;             for (int m = 0; m < 4; ++m) { const float iq = (127.f / QCLIP) * rsqrtf(q1v[m] * (1.f / DM) + EPS);
; #pragma unroll
;                 for (int bj = 0; bj < 2; ++bj) { float hv[8]; unpack8(hr[m][bj], hv); const size_t off = (size_t)(row0 + ai * 128 + m * 16) * DM + col0 + bj * 128;
;                     f32x4 h0 = acc[ai][bj][m][0], h1 = acc[ai][bj][m][1];
; #pragma unroll
;                     for (int e = 0; e < 4; ++e) { h0[e] += hv[e]; h1[e] += hv[4 + e]; }
;                     *(u32x4*)(HB + off) = pack8(h0, h1);
;                     f32x4 q0, q1;
; #pragma unroll
;                     for (int ee = 0; ee < 4; ++ee) { q0[ee] = fminf(fmaxf(rintf(h0[ee] * iq), -127.f), 127.f); q1[ee] = fminf(fmaxf(rintf(h1[ee] * iq), -127.f), 127.f); }
;                     *(u32x2*)(HQ + off) = pack8_i8(q0, q1); } }
	v_cvt_i32_f32_e32 v100, v101
	v_perm_b32 v99, v102, v99, s51
	v_fmamk_f32 v102, v209, 0x39800000, v185
	v_cvt_i32_f32_sdwa v101, v103 dst_sel:WORD_1 dst_unused:UNUSED_PAD src0_sel:DWORD
	v_mul_f32_e32 v103, 0x4b800000, v102
	v_cmp_gt_f32_e32 vcc, s49, v102
	v_lshlrev_b32_e32 v100, 8, v100
	v_and_b32_e32 v100, 0xff00, v100
	v_cndmask_b32_e32 v102, v102, v103, vcc
	v_rsq_f32_e32 v102, v102
	v_and_b32_e32 v101, 0xff0000, v101
	v_or3_b32 v99, v99, v100, v101
	v_lshl_add_u64 v[100:101], s[16:17], 0, v[114:115]
	global_store_dwordx2 v[100:101], v[98:99], off
	v_mul_f32_e32 v98, 0x45800000, v102
	v_cndmask_b32_e32 v98, v102, v98, vcc
	v_lshlrev_b32_e32 v101, 16, v142
	v_and_b32_e32 v102, 0xffff0000, v142
	v_lshlrev_b32_e32 v103, 16, v143
	v_and_b32_e32 v104, 0xffff0000, v143
	v_lshlrev_b32_e32 v105, 16, v144
	v_and_b32_e32 v106, 0xffff0000, v144
	v_lshlrev_b32_e32 v107, 16, v145
	v_mul_f32_e32 v100, 0x41e1c71c, v98
	v_and_b32_e32 v108, 0xffff0000, v145
	v_add_f32_e32 v94, v94, v101
	v_add_f32_e32 v101, v90, v105
	v_add_f32_e32 v95, v95, v102
	v_add_f32_e32 v102, v91, v106
	v_add_f32_e32 v96, v96, v103
	v_add_f32_e32 v103, v92, v107
	v_add_f32_e32 v97, v97, v104
	v_cvt_pk_bf16_f32 v90, v94, v95
	v_cvt_pk_bf16_f32 v91, v96, v97
	v_cvt_pk_bf16_f32 v92, v101, v102
	v_add_f32_e32 v104, v93, v108
	v_cvt_pk_bf16_f32 v93, v103, v104
	global_store_dwordx4 v[176:177], v[90:93], off
	v_lshlrev_b64 v[98:99], 12, v[174:175]
	v_lshl_add_u64 v[98:99], v[98:99], 0, v[162:163]
	v_mul_f32_e32 v92, v95, v100
	v_mul_f32_e32 v90, v94, v100
	v_rndne_f32_e32 v92, v92
	v_mul_f32_e32 v94, v96, v100
	v_mul_f32_e32 v96, v97, v100
	v_rndne_f32_e32 v90, v90
	v_med3_f32 v92, v92, s50, v186
	v_rndne_f32_e32 v94, v94
	v_rndne_f32_e32 v96, v96
	v_med3_f32 v90, v90, s50, v186
	v_med3_f32 v94, v94, s50, v186
	v_med3_f32 v96, v96, s50, v186
	v_cvt_i32_f32_e32 v92, v92
	v_cvt_i32_f32_e32 v90, v90
	v_cvt_i32_f32_sdwa v94, v94 dst_sel:WORD_1 dst_unused:UNUSED_PAD src0_sel:DWORD
	v_cvt_i32_f32_e32 v96, v96
	v_mul_f32_e32 v93, v102, v100
	v_mul_f32_e32 v91, v101, v100
	v_rndne_f32_e32 v93, v93
	v_mul_f32_e32 v95, v103, v100
	v_mul_f32_e32 v97, v104, v100
	v_lshlrev_b32_e32 v92, 8, v92
	v_rndne_f32_e32 v91, v91
	v_med3_f32 v93, v93, s50, v186
	v_rndne_f32_e32 v95, v95
	v_rndne_f32_e32 v97, v97
	v_and_b32_e32 v92, 0xff00, v92
	v_and_b32_e32 v94, 0xff0000, v94
	v_perm_b32 v90, v96, v90, s51
	v_med3_f32 v91, v91, s50, v186
	v_med3_f32 v95, v95, s50, v186
	v_med3_f32 v97, v97, s50, v186
	v_or3_b32 v90, v90, v92, v94
	v_cvt_i32_f32_e32 v92, v93
	v_cvt_i32_f32_e32 v91, v91
	v_cvt_i32_f32_sdwa v93, v95 dst_sel:WORD_1 dst_unused:UNUSED_PAD src0_sel:DWORD
	v_cvt_i32_f32_e32 v94, v97
	v_lshlrev_b32_e32 v92, 8, v92
	v_and_b32_e32 v92, 0xff00, v92
	v_and_b32_e32 v93, 0xff0000, v93
	v_perm_b32 v91, v94, v91, s51
	v_or3_b32 v91, v91, v92, v93
	v_lshl_add_u64 v[92:93], s[16:17], 0, v[98:99]
	global_store_dwordx2 v[92:93], v[90:91], off
	v_lshlrev_b32_e32 v90, 16, v138
	v_and_b32_e32 v91, 0xffff0000, v138
	v_lshlrev_b32_e32 v92, 16, v139
	v_and_b32_e32 v93, 0xffff0000, v139
	v_lshlrev_b32_e32 v94, 16, v140
	v_and_b32_e32 v95, 0xffff0000, v140
	v_lshlrev_b32_e32 v96, 16, v141
	v_or_b32_e32 v98, 0x80, v98
	v_and_b32_e32 v97, 0xffff0000, v141
	v_add_f32_e32 v90, v86, v90
	v_add_f32_e32 v94, v82, v94
	v_add_f32_e32 v91, v87, v91
	v_add_f32_e32 v95, v83, v95
	v_add_f32_e32 v88, v88, v92
	v_add_f32_e32 v92, v84, v96
	v_add_f32_e32 v89, v89, v93
	v_cvt_pk_bf16_f32 v82, v90, v91
	v_cvt_pk_bf16_f32 v83, v88, v89
	v_cvt_pk_bf16_f32 v84, v94, v95
	v_lshl_add_u64 v[86:87], v[98:99], 1, s[14:15]
	v_add_f32_e32 v93, v85, v97
	v_cvt_pk_bf16_f32 v85, v92, v93
	global_store_dwordx4 v[86:87], v[82:85], off
	v_mul_f32_e32 v86, v88, v100
	v_mul_f32_e32 v88, v89, v100
	v_mul_f32_e32 v84, v91, v100
	v_mul_f32_e32 v82, v90, v100
	v_rndne_f32_e32 v84, v84
	v_rndne_f32_e32 v82, v82
	v_med3_f32 v84, v84, s50, v186
	v_rndne_f32_e32 v86, v86
	v_rndne_f32_e32 v88, v88
	v_med3_f32 v82, v82, s50, v186
	v_med3_f32 v86, v86, s50, v186
	v_med3_f32 v88, v88, s50, v186
	v_cvt_i32_f32_e32 v84, v84
	v_cvt_i32_f32_e32 v82, v82
	v_cvt_i32_f32_sdwa v86, v86 dst_sel:WORD_1 dst_unused:UNUSED_PAD src0_sel:DWORD
	v_cvt_i32_f32_e32 v88, v88
	v_mul_f32_e32 v83, v94, v100
	v_mul_f32_e32 v89, v93, v100
	v_rndne_f32_e32 v83, v83
	v_rndne_f32_e32 v89, v89
	v_lshlrev_b32_e32 v84, 8, v84
	v_med3_f32 v83, v83, s50, v186
	v_med3_f32 v89, v89, s50, v186
	v_and_b32_e32 v84, 0xff00, v84
	v_and_b32_e32 v86, 0xff0000, v86
	v_perm_b32 v82, v88, v82, s51
	v_or3_b32 v82, v82, v84, v86
	v_cvt_i32_f32_e32 v83, v83
	v_cvt_i32_f32_e32 v86, v89
	v_mul_f32_e32 v85, v95, v100
	v_rndne_f32_e32 v85, v85
	v_mul_f32_e32 v87, v92, v100
	v_med3_f32 v85, v85, s50, v186
	v_rndne_f32_e32 v87, v87
	v_med3_f32 v87, v87, s50, v186
	v_cvt_i32_f32_e32 v84, v85
	v_perm_b32 v83, v86, v83, s51
	v_fmamk_f32 v86, v167, 0x39800000, v185
	v_cvt_i32_f32_sdwa v85, v87 dst_sel:WORD_1 dst_unused:UNUSED_PAD src0_sel:DWORD
	v_mul_f32_e32 v87, 0x4b800000, v86
	v_cmp_gt_f32_e32 vcc, s49, v86
	v_lshlrev_b32_e32 v84, 8, v84
	v_and_b32_e32 v84, 0xff00, v84
	v_cndmask_b32_e32 v86, v86, v87, vcc
	v_rsq_f32_e32 v86, v86
	v_and_b32_e32 v85, 0xff0000, v85
	v_or3_b32 v83, v83, v84, v85
	v_lshl_add_u64 v[84:85], s[16:17], 0, v[98:99]
	global_store_dwordx2 v[84:85], v[82:83], off
	v_mul_f32_e32 v82, 0x45800000, v86
	v_cndmask_b32_e32 v82, v86, v82, vcc
	v_lshlrev_b32_e32 v85, 16, v134
	v_and_b32_e32 v86, 0xffff0000, v134
	v_lshlrev_b32_e32 v87, 16, v135
	v_and_b32_e32 v88, 0xffff0000, v135
	v_lshlrev_b32_e32 v89, 16, v136
	v_and_b32_e32 v90, 0xffff0000, v136
	v_lshlrev_b32_e32 v91, 16, v137
; __device__ __forceinline__ u32x4 pack8(const f32x4 a, const f32x4 b) { u32x4 w; w.x = cvt_pk_bf16(a[0], a[1]); w.y = cvt_pk_bf16(a[2], a[3]); w.z = cvt_pk_bf16(b[0], b[1]); w.w = cvt_pk_bf16(b[2], b[3]); return w; }
;     __device__ __forceinline__ void operator()(const f32x4 (&acc)[2][2][4][2], const pg8::Unit& u, int wr, int wc, int fr, int fq) const {
;     ...
;         for (int ai = 0; ai < 2; ++ai) {
;             u32x4 hr[4][2]; float q1v[4];
; #pragma unroll
;             for (int m = 0; m < 4; ++m) { q1v[m] = rss1[row0 + ai * 128 + m * 16];
; #pragma unroll
;                 for (int bj = 0; bj < 2; ++bj) hr[m][bj] = *(const u32x4*)(HB + (size_t)(row0 + ai * 128 + m * 16) * DM + col0 + bj * 128); }
; #pragma unroll
;             for (int m = 0; m < 4; ++m) { const float iq = (127.f / QCLIP) * rsqrtf(q1v[m] * (1.f / DM) + EPS);
; #pragma unroll
;                 for (int bj = 0; bj < 2; ++bj) { float hv[8]; unpack8(hr[m][bj], hv); const size_t off = (size_t)(row0 + ai * 128 + m * 16) * DM + col0 + bj * 128;
;                     f32x4 h0 = acc[ai][bj][m][0], h1 = acc[ai][bj][m][1];
; #pragma unroll
;                     for (int e = 0; e < 4; ++e) { h0[e] += hv[e]; h1[e] += hv[4 + e]; }
;                     *(u32x4*)(HB + off) = pack8(h0, h1);
;                     f32x4 q0, q1;
; #pragma unroll
;                     for (int ee = 0; ee < 4; ++ee) { q0[ee] = fminf(fmaxf(rintf(h0[ee] * iq), -127.f), 127.f); q1[ee] = fminf(fmaxf(rintf(h1[ee] * iq), -127.f), 127.f); }
;                     *(u32x2*)(HQ + off) = pack8_i8(q0, q1); } }
	v_mul_f32_e32 v84, 0x41e1c71c, v82
	v_and_b32_e32 v92, 0xffff0000, v137
	v_add_f32_e32 v78, v78, v85
	v_add_f32_e32 v85, v74, v89
	v_add_f32_e32 v79, v79, v86
	v_add_f32_e32 v86, v75, v90
	v_add_f32_e32 v80, v80, v87
	v_add_f32_e32 v87, v76, v91
	v_add_f32_e32 v81, v81, v88
	v_cvt_pk_bf16_f32 v74, v78, v79
	v_cvt_pk_bf16_f32 v75, v80, v81
	v_cvt_pk_bf16_f32 v76, v85, v86
	v_add_f32_e32 v88, v77, v92
	v_cvt_pk_bf16_f32 v77, v87, v88
	global_store_dwordx4 v[172:173], v[74:77], off
	v_lshlrev_b64 v[82:83], 12, v[170:171]
	v_lshl_add_u64 v[82:83], v[82:83], 0, v[162:163]
	v_mul_f32_e32 v76, v79, v84
	v_mul_f32_e32 v74, v78, v84
	v_rndne_f32_e32 v76, v76
	v_mul_f32_e32 v78, v80, v84
	v_mul_f32_e32 v80, v81, v84
	v_rndne_f32_e32 v74, v74
	v_med3_f32 v76, v76, s50, v186
	v_rndne_f32_e32 v78, v78
	v_rndne_f32_e32 v80, v80
	v_med3_f32 v74, v74, s50, v186
	v_med3_f32 v78, v78, s50, v186
	v_med3_f32 v80, v80, s50, v186
	v_cvt_i32_f32_e32 v76, v76
	v_cvt_i32_f32_e32 v74, v74
	v_cvt_i32_f32_sdwa v78, v78 dst_sel:WORD_1 dst_unused:UNUSED_PAD src0_sel:DWORD
	v_cvt_i32_f32_e32 v80, v80
	v_mul_f32_e32 v77, v86, v84
	v_mul_f32_e32 v75, v85, v84
	v_rndne_f32_e32 v77, v77
	v_mul_f32_e32 v79, v87, v84
	v_mul_f32_e32 v81, v88, v84
	v_lshlrev_b32_e32 v76, 8, v76
	v_rndne_f32_e32 v75, v75
	v_med3_f32 v77, v77, s50, v186
	v_rndne_f32_e32 v79, v79
	v_rndne_f32_e32 v81, v81
	v_and_b32_e32 v76, 0xff00, v76
	v_and_b32_e32 v78, 0xff0000, v78
	v_perm_b32 v74, v80, v74, s51
	v_med3_f32 v75, v75, s50, v186
	v_med3_f32 v79, v79, s50, v186
	v_med3_f32 v81, v81, s50, v186
	v_or3_b32 v74, v74, v76, v78
	v_cvt_i32_f32_e32 v76, v77
	v_cvt_i32_f32_e32 v75, v75
	v_cvt_i32_f32_sdwa v77, v79 dst_sel:WORD_1 dst_unused:UNUSED_PAD src0_sel:DWORD
	v_cvt_i32_f32_e32 v78, v81
	v_lshlrev_b32_e32 v76, 8, v76
	v_and_b32_e32 v76, 0xff00, v76
	v_and_b32_e32 v77, 0xff0000, v77
	v_perm_b32 v75, v78, v75, s51
	v_or3_b32 v75, v75, v76, v77
	v_lshl_add_u64 v[76:77], s[16:17], 0, v[82:83]
	global_store_dwordx2 v[76:77], v[74:75], off
	v_lshlrev_b32_e32 v74, 16, v130
	v_and_b32_e32 v75, 0xffff0000, v130
	v_lshlrev_b32_e32 v76, 16, v131
	v_and_b32_e32 v77, 0xffff0000, v131
	v_lshlrev_b32_e32 v78, 16, v132
	v_and_b32_e32 v79, 0xffff0000, v132
	v_lshlrev_b32_e32 v80, 16, v133
	v_or_b32_e32 v82, 0x80, v82
	v_and_b32_e32 v81, 0xffff0000, v133
	v_add_f32_e32 v74, v70, v74
	v_add_f32_e32 v78, v66, v78
	v_add_f32_e32 v75, v71, v75
	v_add_f32_e32 v79, v67, v79
	v_add_f32_e32 v72, v72, v76
	v_add_f32_e32 v76, v68, v80
	v_add_f32_e32 v73, v73, v77
	v_cvt_pk_bf16_f32 v66, v74, v75
	v_cvt_pk_bf16_f32 v67, v72, v73
	v_cvt_pk_bf16_f32 v68, v78, v79
	v_lshl_add_u64 v[70:71], v[82:83], 1, s[14:15]
	v_add_f32_e32 v77, v69, v81
	v_cvt_pk_bf16_f32 v69, v76, v77
	global_store_dwordx4 v[70:71], v[66:69], off
	v_mul_f32_e32 v70, v72, v84
	v_mul_f32_e32 v72, v73, v84
	v_mul_f32_e32 v68, v75, v84
	v_mul_f32_e32 v66, v74, v84
	v_rndne_f32_e32 v68, v68
	v_rndne_f32_e32 v66, v66
	v_med3_f32 v68, v68, s50, v186
	v_rndne_f32_e32 v70, v70
	v_rndne_f32_e32 v72, v72
	v_med3_f32 v66, v66, s50, v186
	v_med3_f32 v70, v70, s50, v186
	v_med3_f32 v72, v72, s50, v186
	v_cvt_i32_f32_e32 v68, v68
	v_cvt_i32_f32_e32 v66, v66
	v_cvt_i32_f32_sdwa v70, v70 dst_sel:WORD_1 dst_unused:UNUSED_PAD src0_sel:DWORD
	v_cvt_i32_f32_e32 v72, v72
	v_mul_f32_e32 v69, v79, v84
	v_mul_f32_e32 v67, v78, v84
	v_rndne_f32_e32 v69, v69
	v_mul_f32_e32 v71, v76, v84
	v_mul_f32_e32 v73, v77, v84
	v_lshlrev_b32_e32 v68, 8, v68
	v_rndne_f32_e32 v67, v67
	v_med3_f32 v69, v69, s50, v186
	v_rndne_f32_e32 v71, v71
	v_rndne_f32_e32 v73, v73
	v_and_b32_e32 v68, 0xff00, v68
	v_and_b32_e32 v70, 0xff0000, v70
	v_perm_b32 v66, v72, v66, s51
	v_med3_f32 v67, v67, s50, v186
	v_med3_f32 v71, v71, s50, v186
	v_med3_f32 v73, v73, s50, v186
	v_or3_b32 v66, v66, v68, v70
	v_cvt_i32_f32_e32 v68, v69
	v_cvt_i32_f32_e32 v67, v67
	v_cvt_i32_f32_sdwa v69, v71 dst_sel:WORD_1 dst_unused:UNUSED_PAD src0_sel:DWORD
	v_cvt_i32_f32_e32 v70, v73
	v_lshlrev_b32_e32 v68, 8, v68
	v_and_b32_e32 v68, 0xff00, v68
	v_and_b32_e32 v69, 0xff0000, v69
	v_perm_b32 v67, v70, v67, s51
	v_or3_b32 v67, v67, v68, v69
	v_lshl_add_u64 v[68:69], s[16:17], 0, v[82:83]
	global_store_dwordx2 v[68:69], v[66:67], off
	global_load_dword v68, v[168:169], off offset:512
	v_add_u32_e32 v108, 0x80, v166
	v_ashrrev_i32_e32 v109, 31, v108
	v_lshlrev_b64 v[66:67], 13, v[108:109]
	v_lshl_add_u64 v[110:111], v[164:165], 0, v[66:67]
	global_load_dwordx4 v[96:99], v[110:111], off nt
	global_load_dwordx4 v[100:103], v[110:111], off offset:256 nt
	v_add_u32_e32 v112, 0x90, v166
	v_ashrrev_i32_e32 v113, 31, v112
	v_add_u32_e32 v92, 0xa0, v166
	v_lshlrev_b64 v[66:67], 13, v[112:113]
	v_ashrrev_i32_e32 v93, 31, v92
	v_lshl_add_u64 v[114:115], v[164:165], 0, v[66:67]
	v_lshlrev_b64 v[66:67], 13, v[92:93]
	v_lshl_add_u64 v[90:91], v[164:165], 0, v[66:67]
	global_load_dwordx4 v[104:107], v[114:115], off nt
	global_load_dwordx4 v[82:85], v[114:115], off offset:256 nt
	global_load_dwordx4 v[78:81], v[90:91], off nt
	global_load_dwordx4 v[74:77], v[90:91], off offset:256 nt
	global_load_dword v95, v[168:169], off offset:576
	global_load_dword v116, v[168:169], off offset:640
	global_load_dword v94, v[168:169], off offset:704
	v_add_u32_e32 v88, 0xb0, v166
	v_ashrrev_i32_e32 v89, 31, v88
	v_lshlrev_b64 v[66:67], 13, v[88:89]
	v_lshl_add_u64 v[86:87], v[164:165], 0, v[66:67]
	v_lshlrev_b64 v[108:109], 12, v[108:109]
	v_lshl_add_u64 v[108:109], v[108:109], 0, v[162:163]
	s_waitcnt vmcnt(9)
	v_fmamk_f32 v68, v68, 0x39800000, v185
	v_mul_f32_e32 v69, 0x4b800000, v68
	v_cmp_gt_f32_e32 vcc, s49, v68
	s_waitcnt vmcnt(8)
; __device__ __forceinline__ u32x4 pack8(const f32x4 a, const f32x4 b) { u32x4 w; w.x = cvt_pk_bf16(a[0], a[1]); w.y = cvt_pk_bf16(a[2], a[3]); w.z = cvt_pk_bf16(b[0], b[1]); w.w = cvt_pk_bf16(b[2], b[3]); return w; }
;     __device__ __forceinline__ void operator()(const f32x4 (&acc)[2][2][4][2], const pg8::Unit& u, int wr, int wc, int fr, int fq) const {
;     ...
;             u32x4 hr[4][2]; float q1v[4];
; #pragma unroll
;             for (int m = 0; m < 4; ++m) { q1v[m] = rss1[row0 + ai * 128 + m * 16];
; #pragma unroll
;                 for (int bj = 0; bj < 2; ++bj) hr[m][bj] = *(const u32x4*)(HB + (size_t)(row0 + ai * 128 + m * 16) * DM + col0 + bj * 128); }
; #pragma unroll
;             for (int m = 0; m < 4; ++m) { const float iq = (127.f / QCLIP) * rsqrtf(q1v[m] * (1.f / DM) + EPS);
; #pragma unroll
;                 for (int bj = 0; bj < 2; ++bj) { float hv[8]; unpack8(hr[m][bj], hv); const size_t off = (size_t)(row0 + ai * 128 + m * 16) * DM + col0 + bj * 128;
;                     f32x4 h0 = acc[ai][bj][m][0], h1 = acc[ai][bj][m][1];
; #pragma unroll
;                     for (int e = 0; e < 4; ++e) { h0[e] += hv[e]; h1[e] += hv[4 + e]; }
;                     *(u32x4*)(HB + off) = pack8(h0, h1);
;                     f32x4 q0, q1;
; #pragma unroll
;                     for (int ee = 0; ee < 4; ++ee) { q0[ee] = fminf(fmaxf(rintf(h0[ee] * iq), -127.f), 127.f); q1[ee] = fminf(fmaxf(rintf(h1[ee] * iq), -127.f), 127.f); }
;                     *(u32x2*)(HQ + off) = pack8_i8(q0, q1); } }
	v_lshlrev_b32_e32 v119, 16, v97
	v_cndmask_b32_e32 v68, v68, v69, vcc
	v_rsq_f32_e32 v117, v68
	v_and_b32_e32 v97, 0xffff0000, v97
	v_lshlrev_b32_e32 v120, 16, v98
	v_and_b32_e32 v98, 0xffff0000, v98
	v_mul_f32_e32 v118, 0x45800000, v117
	v_cndmask_b32_e32 v117, v117, v118, vcc
	v_lshlrev_b32_e32 v118, 16, v96
	v_and_b32_e32 v96, 0xffff0000, v96
	v_lshlrev_b32_e32 v121, 16, v99
	global_load_dwordx4 v[70:73], v[86:87], off nt
	global_load_dwordx4 v[66:69], v[86:87], off offset:256 nt
	v_mul_f32_e32 v117, 0x41e1c71c, v117
	v_and_b32_e32 v99, 0xffff0000, v99
	v_add_f32_e32 v62, v62, v118
	v_add_f32_e32 v118, v58, v120
	v_add_f32_e32 v63, v63, v96
	v_add_f32_e32 v96, v59, v98
	v_add_f32_e32 v64, v64, v119
	v_add_f32_e32 v98, v60, v121
	v_add_f32_e32 v65, v65, v97
	v_cvt_pk_bf16_f32 v58, v62, v63
	v_cvt_pk_bf16_f32 v59, v64, v65
	v_cvt_pk_bf16_f32 v60, v118, v96
	v_add_f32_e32 v97, v61, v99
	v_cvt_pk_bf16_f32 v61, v98, v97
	global_store_dwordx4 v[110:111], v[58:61], off
	s_nop 1
	v_mul_f32_e32 v60, v63, v117
	v_mul_f32_e32 v58, v62, v117
	v_rndne_f32_e32 v60, v60
	v_mul_f32_e32 v62, v64, v117
	v_mul_f32_e32 v64, v65, v117
	v_rndne_f32_e32 v58, v58
	v_med3_f32 v60, v60, s50, v186
	v_rndne_f32_e32 v62, v62
	v_rndne_f32_e32 v64, v64
	v_med3_f32 v58, v58, s50, v186
	v_med3_f32 v62, v62, s50, v186
	v_med3_f32 v64, v64, s50, v186
	v_cvt_i32_f32_e32 v60, v60
	v_cvt_i32_f32_e32 v58, v58
	v_cvt_i32_f32_sdwa v62, v62 dst_sel:WORD_1 dst_unused:UNUSED_PAD src0_sel:DWORD
	v_cvt_i32_f32_e32 v64, v64
	v_mul_f32_e32 v61, v96, v117
	v_mul_f32_e32 v59, v118, v117
	v_rndne_f32_e32 v61, v61
	v_mul_f32_e32 v63, v98, v117
	v_mul_f32_e32 v65, v97, v117
	v_lshlrev_b32_e32 v60, 8, v60
	v_rndne_f32_e32 v59, v59
	v_med3_f32 v61, v61, s50, v186
	v_rndne_f32_e32 v63, v63
	v_rndne_f32_e32 v65, v65
	v_and_b32_e32 v60, 0xff00, v60
	v_and_b32_e32 v62, 0xff0000, v62
	v_perm_b32 v58, v64, v58, s51
	v_med3_f32 v59, v59, s50, v186
	v_med3_f32 v63, v63, s50, v186
	v_med3_f32 v65, v65, s50, v186
	v_or3_b32 v58, v58, v60, v62
	v_cvt_i32_f32_e32 v60, v61
	v_cvt_i32_f32_e32 v59, v59
	v_cvt_i32_f32_sdwa v61, v63 dst_sel:WORD_1 dst_unused:UNUSED_PAD src0_sel:DWORD
	v_cvt_i32_f32_e32 v62, v65
	v_lshlrev_b32_e32 v60, 8, v60
	v_and_b32_e32 v60, 0xff00, v60
	v_and_b32_e32 v61, 0xff0000, v61
	v_perm_b32 v59, v62, v59, s51
	v_or3_b32 v59, v59, v60, v61
	v_lshl_add_u64 v[60:61], s[16:17], 0, v[108:109]
	global_store_dwordx2 v[60:61], v[58:59], off
	s_waitcnt vmcnt(11)
	v_lshlrev_b32_e32 v58, 16, v100
	v_and_b32_e32 v59, 0xffff0000, v100
	v_lshlrev_b32_e32 v60, 16, v101
	v_and_b32_e32 v61, 0xffff0000, v101
	v_lshlrev_b32_e32 v62, 16, v102
	v_and_b32_e32 v63, 0xffff0000, v102
	v_lshlrev_b32_e32 v64, 16, v103
	v_or_b32_e32 v108, 0x80, v108
	v_and_b32_e32 v65, 0xffff0000, v103
	v_add_f32_e32 v58, v54, v58
	v_add_f32_e32 v62, v50, v62
	v_add_f32_e32 v59, v55, v59
	v_add_f32_e32 v63, v51, v63
	v_add_f32_e32 v56, v56, v60
	v_add_f32_e32 v60, v52, v64
	v_add_f32_e32 v57, v57, v61
	v_cvt_pk_bf16_f32 v50, v58, v59
	v_cvt_pk_bf16_f32 v51, v56, v57
	v_cvt_pk_bf16_f32 v52, v62, v63
	v_lshl_add_u64 v[54:55], v[108:109], 1, s[14:15]
	v_add_f32_e32 v61, v53, v65
	v_cvt_pk_bf16_f32 v53, v60, v61
	global_store_dwordx4 v[54:55], v[50:53], off
	v_mul_f32_e32 v54, v56, v117
	v_mul_f32_e32 v56, v57, v117
	v_mul_f32_e32 v52, v59, v117
	v_mul_f32_e32 v50, v58, v117
	v_rndne_f32_e32 v52, v52
	v_rndne_f32_e32 v50, v50
	v_med3_f32 v52, v52, s50, v186
	v_rndne_f32_e32 v54, v54
	v_rndne_f32_e32 v56, v56
	v_med3_f32 v50, v50, s50, v186
	v_med3_f32 v54, v54, s50, v186
	v_med3_f32 v56, v56, s50, v186
	v_cvt_i32_f32_e32 v52, v52
	v_cvt_i32_f32_e32 v50, v50
	v_cvt_i32_f32_sdwa v54, v54 dst_sel:WORD_1 dst_unused:UNUSED_PAD src0_sel:DWORD
	v_cvt_i32_f32_e32 v56, v56
	v_mul_f32_e32 v51, v62, v117
	v_mul_f32_e32 v57, v61, v117
	v_rndne_f32_e32 v51, v51
	v_rndne_f32_e32 v57, v57
	v_lshlrev_b32_e32 v52, 8, v52
	v_med3_f32 v51, v51, s50, v186
	v_med3_f32 v57, v57, s50, v186
	v_and_b32_e32 v52, 0xff00, v52
	v_and_b32_e32 v54, 0xff0000, v54
	v_perm_b32 v50, v56, v50, s51
	v_or3_b32 v50, v50, v52, v54
	v_cvt_i32_f32_e32 v51, v51
	v_cvt_i32_f32_e32 v54, v57
	v_mul_f32_e32 v53, v63, v117
	v_rndne_f32_e32 v53, v53
	v_mul_f32_e32 v55, v60, v117
	v_med3_f32 v53, v53, s50, v186
	v_rndne_f32_e32 v55, v55
	v_med3_f32 v55, v55, s50, v186
	v_cvt_i32_f32_e32 v52, v53
	v_perm_b32 v51, v54, v51, s51
	s_waitcnt vmcnt(7)
; __device__ __forceinline__ u32x4 pack8(const f32x4 a, const f32x4 b) { u32x4 w; w.x = cvt_pk_bf16(a[0], a[1]); w.y = cvt_pk_bf16(a[2], a[3]); w.z = cvt_pk_bf16(b[0], b[1]); w.w = cvt_pk_bf16(b[2], b[3]); return w; }
;     __device__ __forceinline__ void operator()(const f32x4 (&acc)[2][2][4][2], const pg8::Unit& u, int wr, int wc, int fr, int fq) const {
;     ...
;             for (int m = 0; m < 4; ++m) { const float iq = (127.f / QCLIP) * rsqrtf(q1v[m] * (1.f / DM) + EPS);
; #pragma unroll
;                 for (int bj = 0; bj < 2; ++bj) { float hv[8]; unpack8(hr[m][bj], hv); const size_t off = (size_t)(row0 + ai * 128 + m * 16) * DM + col0 + bj * 128;
;                     f32x4 h0 = acc[ai][bj][m][0], h1 = acc[ai][bj][m][1];
; #pragma unroll
;                     for (int e = 0; e < 4; ++e) { h0[e] += hv[e]; h1[e] += hv[4 + e]; }
;                     *(u32x4*)(HB + off) = pack8(h0, h1);
;                     f32x4 q0, q1;
; #pragma unroll
;                     for (int ee = 0; ee < 4; ++ee) { q0[ee] = fminf(fmaxf(rintf(h0[ee] * iq), -127.f), 127.f); q1[ee] = fminf(fmaxf(rintf(h1[ee] * iq), -127.f), 127.f); }
;                     *(u32x2*)(HQ + off) = pack8_i8(q0, q1); } }
	v_fmamk_f32 v54, v95, 0x39800000, v185
	v_cvt_i32_f32_sdwa v53, v55 dst_sel:WORD_1 dst_unused:UNUSED_PAD src0_sel:DWORD
	v_mul_f32_e32 v55, 0x4b800000, v54
	v_cmp_gt_f32_e32 vcc, s49, v54
	v_lshlrev_b32_e32 v52, 8, v52
	v_and_b32_e32 v52, 0xff00, v52
	v_cndmask_b32_e32 v54, v54, v55, vcc
	v_rsq_f32_e32 v54, v54
	v_and_b32_e32 v53, 0xff0000, v53
	v_or3_b32 v51, v51, v52, v53
	v_lshl_add_u64 v[52:53], s[16:17], 0, v[108:109]
	global_store_dwordx2 v[52:53], v[50:51], off
	v_mul_f32_e32 v50, 0x45800000, v54
	v_cndmask_b32_e32 v50, v54, v50, vcc
	v_lshlrev_b32_e32 v53, 16, v104
	v_and_b32_e32 v54, 0xffff0000, v104
	v_lshlrev_b32_e32 v55, 16, v105
	v_and_b32_e32 v56, 0xffff0000, v105
	v_lshlrev_b32_e32 v57, 16, v106
	v_and_b32_e32 v58, 0xffff0000, v106
	v_lshlrev_b32_e32 v59, 16, v107
	v_mul_f32_e32 v52, 0x41e1c71c, v50
	v_and_b32_e32 v60, 0xffff0000, v107
	v_add_f32_e32 v46, v46, v53
	v_add_f32_e32 v53, v42, v57
	v_add_f32_e32 v47, v47, v54
	v_add_f32_e32 v54, v43, v58
	v_add_f32_e32 v48, v48, v55
	v_add_f32_e32 v55, v44, v59
	v_add_f32_e32 v49, v49, v56
	v_cvt_pk_bf16_f32 v42, v46, v47
	v_cvt_pk_bf16_f32 v43, v48, v49
	v_cvt_pk_bf16_f32 v44, v53, v54
	v_add_f32_e32 v56, v45, v60
	v_cvt_pk_bf16_f32 v45, v55, v56
	global_store_dwordx4 v[114:115], v[42:45], off
	v_lshlrev_b64 v[50:51], 12, v[112:113]
	v_lshl_add_u64 v[50:51], v[50:51], 0, v[162:163]
	v_mul_f32_e32 v44, v47, v52
	v_mul_f32_e32 v42, v46, v52
	v_rndne_f32_e32 v44, v44
	v_mul_f32_e32 v46, v48, v52
	v_mul_f32_e32 v48, v49, v52
	v_rndne_f32_e32 v42, v42
	v_med3_f32 v44, v44, s50, v186
	v_rndne_f32_e32 v46, v46
	v_rndne_f32_e32 v48, v48
	v_med3_f32 v42, v42, s50, v186
	v_med3_f32 v46, v46, s50, v186
	v_med3_f32 v48, v48, s50, v186
	v_cvt_i32_f32_e32 v44, v44
	v_cvt_i32_f32_e32 v42, v42
	v_cvt_i32_f32_sdwa v46, v46 dst_sel:WORD_1 dst_unused:UNUSED_PAD src0_sel:DWORD
	v_cvt_i32_f32_e32 v48, v48
	v_mul_f32_e32 v45, v54, v52
	v_mul_f32_e32 v43, v53, v52
	v_rndne_f32_e32 v45, v45
	v_mul_f32_e32 v47, v55, v52
	v_mul_f32_e32 v49, v56, v52
	v_lshlrev_b32_e32 v44, 8, v44
	v_rndne_f32_e32 v43, v43
	v_med3_f32 v45, v45, s50, v186
	v_rndne_f32_e32 v47, v47
	v_rndne_f32_e32 v49, v49
	v_and_b32_e32 v44, 0xff00, v44
	v_and_b32_e32 v46, 0xff0000, v46
	v_perm_b32 v42, v48, v42, s51
	v_med3_f32 v43, v43, s50, v186
	v_med3_f32 v47, v47, s50, v186
	v_med3_f32 v49, v49, s50, v186
	v_or3_b32 v42, v42, v44, v46
	v_cvt_i32_f32_e32 v44, v45
	v_cvt_i32_f32_e32 v43, v43
	v_cvt_i32_f32_sdwa v45, v47 dst_sel:WORD_1 dst_unused:UNUSED_PAD src0_sel:DWORD
	v_cvt_i32_f32_e32 v46, v49
	v_lshlrev_b32_e32 v44, 8, v44
	v_and_b32_e32 v44, 0xff00, v44
	v_and_b32_e32 v45, 0xff0000, v45
	v_perm_b32 v43, v46, v43, s51
	v_or3_b32 v43, v43, v44, v45
	v_lshl_add_u64 v[44:45], s[16:17], 0, v[50:51]
	global_store_dwordx2 v[44:45], v[42:43], off
	v_lshlrev_b32_e32 v42, 16, v82
	v_and_b32_e32 v43, 0xffff0000, v82
	v_lshlrev_b32_e32 v44, 16, v83
	v_and_b32_e32 v45, 0xffff0000, v83
	v_lshlrev_b32_e32 v46, 16, v84
	v_and_b32_e32 v47, 0xffff0000, v84
	v_lshlrev_b32_e32 v48, 16, v85
	v_or_b32_e32 v50, 0x80, v50
	v_and_b32_e32 v49, 0xffff0000, v85
	v_add_f32_e32 v42, v38, v42
	v_add_f32_e32 v46, v34, v46
	v_add_f32_e32 v43, v39, v43
	v_add_f32_e32 v47, v35, v47
	v_add_f32_e32 v40, v40, v44
	v_add_f32_e32 v44, v36, v48
	v_add_f32_e32 v41, v41, v45
	v_cvt_pk_bf16_f32 v34, v42, v43
	v_cvt_pk_bf16_f32 v35, v40, v41
	v_cvt_pk_bf16_f32 v36, v46, v47
	v_lshl_add_u64 v[38:39], v[50:51], 1, s[14:15]
	v_add_f32_e32 v45, v37, v49
	v_cvt_pk_bf16_f32 v37, v44, v45
	global_store_dwordx4 v[38:39], v[34:37], off
	v_mul_f32_e32 v38, v40, v52
	v_mul_f32_e32 v40, v41, v52
	v_mul_f32_e32 v36, v43, v52
	v_mul_f32_e32 v34, v42, v52
	v_rndne_f32_e32 v36, v36
	v_rndne_f32_e32 v34, v34
	v_med3_f32 v36, v36, s50, v186
	v_rndne_f32_e32 v38, v38
	v_rndne_f32_e32 v40, v40
	v_med3_f32 v34, v34, s50, v186
	v_med3_f32 v38, v38, s50, v186
	v_med3_f32 v40, v40, s50, v186
	v_cvt_i32_f32_e32 v36, v36
	v_cvt_i32_f32_e32 v34, v34
	v_cvt_i32_f32_sdwa v38, v38 dst_sel:WORD_1 dst_unused:UNUSED_PAD src0_sel:DWORD
	v_cvt_i32_f32_e32 v40, v40
	v_mul_f32_e32 v35, v46, v52
	v_mul_f32_e32 v41, v45, v52
	v_rndne_f32_e32 v35, v35
	v_rndne_f32_e32 v41, v41
	v_lshlrev_b32_e32 v36, 8, v36
	v_med3_f32 v35, v35, s50, v186
	v_med3_f32 v41, v41, s50, v186
	v_and_b32_e32 v36, 0xff00, v36
	v_and_b32_e32 v38, 0xff0000, v38
	v_perm_b32 v34, v40, v34, s51
	v_or3_b32 v34, v34, v36, v38
	v_cvt_i32_f32_e32 v35, v35
	v_cvt_i32_f32_e32 v38, v41
	v_mul_f32_e32 v37, v47, v52
	v_rndne_f32_e32 v37, v37
	v_mul_f32_e32 v39, v44, v52
	v_med3_f32 v37, v37, s50, v186
	v_rndne_f32_e32 v39, v39
	v_med3_f32 v39, v39, s50, v186
	v_cvt_i32_f32_e32 v36, v37
	v_perm_b32 v35, v38, v35, s51
	s_waitcnt vmcnt(10)
; __device__ __forceinline__ u32x4 pack8(const f32x4 a, const f32x4 b) { u32x4 w; w.x = cvt_pk_bf16(a[0], a[1]); w.y = cvt_pk_bf16(a[2], a[3]); w.z = cvt_pk_bf16(b[0], b[1]); w.w = cvt_pk_bf16(b[2], b[3]); return w; }
;     __device__ __forceinline__ void operator()(const f32x4 (&acc)[2][2][4][2], const pg8::Unit& u, int wr, int wc, int fr, int fq) const {
;     ...
;             for (int m = 0; m < 4; ++m) { const float iq = (127.f / QCLIP) * rsqrtf(q1v[m] * (1.f / DM) + EPS);
; #pragma unroll
;                 for (int bj = 0; bj < 2; ++bj) { float hv[8]; unpack8(hr[m][bj], hv); const size_t off = (size_t)(row0 + ai * 128 + m * 16) * DM + col0 + bj * 128;
;                     f32x4 h0 = acc[ai][bj][m][0], h1 = acc[ai][bj][m][1];
; #pragma unroll
;                     for (int e = 0; e < 4; ++e) { h0[e] += hv[e]; h1[e] += hv[4 + e]; }
;                     *(u32x4*)(HB + off) = pack8(h0, h1);
;                     f32x4 q0, q1;
; #pragma unroll
;                     for (int ee = 0; ee < 4; ++ee) { q0[ee] = fminf(fmaxf(rintf(h0[ee] * iq), -127.f), 127.f); q1[ee] = fminf(fmaxf(rintf(h1[ee] * iq), -127.f), 127.f); }
;                     *(u32x2*)(HQ + off) = pack8_i8(q0, q1); } }
	v_fmamk_f32 v38, v116, 0x39800000, v185
	v_cvt_i32_f32_sdwa v37, v39 dst_sel:WORD_1 dst_unused:UNUSED_PAD src0_sel:DWORD
	v_mul_f32_e32 v39, 0x4b800000, v38
	v_cmp_gt_f32_e32 vcc, s49, v38
	v_lshlrev_b32_e32 v36, 8, v36
	v_and_b32_e32 v36, 0xff00, v36
	v_cndmask_b32_e32 v38, v38, v39, vcc
	v_rsq_f32_e32 v38, v38
	v_and_b32_e32 v37, 0xff0000, v37
	v_or3_b32 v35, v35, v36, v37
	v_lshl_add_u64 v[36:37], s[16:17], 0, v[50:51]
	global_store_dwordx2 v[36:37], v[34:35], off
	v_mul_f32_e32 v34, 0x45800000, v38
	v_cndmask_b32_e32 v34, v38, v34, vcc
	v_lshlrev_b32_e32 v37, 16, v78
	v_and_b32_e32 v38, 0xffff0000, v78
	v_lshlrev_b32_e32 v39, 16, v79
	v_and_b32_e32 v40, 0xffff0000, v79
	v_lshlrev_b32_e32 v41, 16, v80
	v_and_b32_e32 v42, 0xffff0000, v80
	v_lshlrev_b32_e32 v43, 16, v81
	v_mul_f32_e32 v36, 0x41e1c71c, v34
	v_and_b32_e32 v44, 0xffff0000, v81
	v_add_f32_e32 v30, v30, v37
	v_add_f32_e32 v37, v26, v41
	v_add_f32_e32 v31, v31, v38
	v_add_f32_e32 v38, v27, v42
	v_add_f32_e32 v32, v32, v39
	v_add_f32_e32 v39, v28, v43
	v_add_f32_e32 v33, v33, v40
	v_cvt_pk_bf16_f32 v26, v30, v31
	v_cvt_pk_bf16_f32 v27, v32, v33
	v_cvt_pk_bf16_f32 v28, v37, v38
	v_add_f32_e32 v40, v29, v44
	v_cvt_pk_bf16_f32 v29, v39, v40
	global_store_dwordx4 v[90:91], v[26:29], off
	v_lshlrev_b64 v[34:35], 12, v[92:93]
	v_lshl_add_u64 v[34:35], v[34:35], 0, v[162:163]
	v_mul_f32_e32 v28, v31, v36
	v_mul_f32_e32 v26, v30, v36
	v_rndne_f32_e32 v28, v28
	v_mul_f32_e32 v30, v32, v36
	v_mul_f32_e32 v32, v33, v36
	v_rndne_f32_e32 v26, v26
	v_med3_f32 v28, v28, s50, v186
	v_rndne_f32_e32 v30, v30
	v_rndne_f32_e32 v32, v32
	v_med3_f32 v26, v26, s50, v186
	v_med3_f32 v30, v30, s50, v186
	v_med3_f32 v32, v32, s50, v186
	v_cvt_i32_f32_e32 v28, v28
	v_cvt_i32_f32_e32 v26, v26
	v_cvt_i32_f32_sdwa v30, v30 dst_sel:WORD_1 dst_unused:UNUSED_PAD src0_sel:DWORD
	v_cvt_i32_f32_e32 v32, v32
	v_mul_f32_e32 v29, v38, v36
	v_mul_f32_e32 v27, v37, v36
	v_rndne_f32_e32 v29, v29
	v_mul_f32_e32 v31, v39, v36
	v_mul_f32_e32 v33, v40, v36
	v_lshlrev_b32_e32 v28, 8, v28
	v_rndne_f32_e32 v27, v27
	v_med3_f32 v29, v29, s50, v186
	v_rndne_f32_e32 v31, v31
	v_rndne_f32_e32 v33, v33
	v_and_b32_e32 v28, 0xff00, v28
	v_and_b32_e32 v30, 0xff0000, v30
	v_perm_b32 v26, v32, v26, s51
	v_med3_f32 v27, v27, s50, v186
	v_med3_f32 v31, v31, s50, v186
	v_med3_f32 v33, v33, s50, v186
	v_or3_b32 v26, v26, v28, v30
	v_cvt_i32_f32_e32 v28, v29
	v_cvt_i32_f32_e32 v27, v27
	v_cvt_i32_f32_sdwa v29, v31 dst_sel:WORD_1 dst_unused:UNUSED_PAD src0_sel:DWORD
	v_cvt_i32_f32_e32 v30, v33
	v_lshlrev_b32_e32 v28, 8, v28
	v_and_b32_e32 v28, 0xff00, v28
	v_and_b32_e32 v29, 0xff0000, v29
	v_perm_b32 v27, v30, v27, s51
	v_or3_b32 v27, v27, v28, v29
	v_lshl_add_u64 v[28:29], s[16:17], 0, v[34:35]
	global_store_dwordx2 v[28:29], v[26:27], off
	v_lshlrev_b32_e32 v26, 16, v74
	v_and_b32_e32 v27, 0xffff0000, v74
	v_lshlrev_b32_e32 v28, 16, v75
	v_and_b32_e32 v29, 0xffff0000, v75
	v_lshlrev_b32_e32 v30, 16, v76
	v_and_b32_e32 v31, 0xffff0000, v76
	v_lshlrev_b32_e32 v32, 16, v77
	v_or_b32_e32 v34, 0x80, v34
	v_and_b32_e32 v33, 0xffff0000, v77
	v_add_f32_e32 v26, v22, v26
	v_add_f32_e32 v30, v18, v30
	v_add_f32_e32 v27, v23, v27
	v_add_f32_e32 v31, v19, v31
	v_add_f32_e32 v24, v24, v28
	v_add_f32_e32 v28, v20, v32
	v_add_f32_e32 v25, v25, v29
	v_cvt_pk_bf16_f32 v18, v26, v27
	v_cvt_pk_bf16_f32 v19, v24, v25
	v_cvt_pk_bf16_f32 v20, v30, v31
	v_lshl_add_u64 v[22:23], v[34:35], 1, s[14:15]
	v_add_f32_e32 v29, v21, v33
	v_cvt_pk_bf16_f32 v21, v28, v29
	global_store_dwordx4 v[22:23], v[18:21], off
	v_mul_f32_e32 v22, v24, v36
	v_mul_f32_e32 v24, v25, v36
	v_mul_f32_e32 v20, v27, v36
	v_mul_f32_e32 v18, v26, v36
	v_rndne_f32_e32 v20, v20
	v_rndne_f32_e32 v18, v18
	v_med3_f32 v20, v20, s50, v186
	v_rndne_f32_e32 v22, v22
	v_rndne_f32_e32 v24, v24
	v_med3_f32 v18, v18, s50, v186
	v_med3_f32 v22, v22, s50, v186
	v_med3_f32 v24, v24, s50, v186
	v_cvt_i32_f32_e32 v20, v20
	v_cvt_i32_f32_e32 v18, v18
	v_cvt_i32_f32_sdwa v22, v22 dst_sel:WORD_1 dst_unused:UNUSED_PAD src0_sel:DWORD
	v_cvt_i32_f32_e32 v24, v24
	v_mul_f32_e32 v19, v30, v36
	v_mul_f32_e32 v25, v29, v36
	v_rndne_f32_e32 v19, v19
	v_rndne_f32_e32 v25, v25
	v_lshlrev_b32_e32 v20, 8, v20
	v_med3_f32 v19, v19, s50, v186
	v_med3_f32 v25, v25, s50, v186
	v_and_b32_e32 v20, 0xff00, v20
	v_and_b32_e32 v22, 0xff0000, v22
	v_perm_b32 v18, v24, v18, s51
	v_or3_b32 v18, v18, v20, v22
	v_cvt_i32_f32_e32 v19, v19
	v_cvt_i32_f32_e32 v22, v25
	v_mul_f32_e32 v21, v31, v36
	v_rndne_f32_e32 v21, v21
	v_mul_f32_e32 v23, v28, v36
	v_med3_f32 v21, v21, s50, v186
	v_rndne_f32_e32 v23, v23
	v_med3_f32 v23, v23, s50, v186
	v_cvt_i32_f32_e32 v20, v21
	v_perm_b32 v19, v22, v19, s51
	s_waitcnt vmcnt(13)
; #define PG8_BAR __builtin_amdgcn_s_barrier()
; __device__ __forceinline__ u32x4 pack8(const f32x4 a, const f32x4 b) { u32x4 w; w.x = cvt_pk_bf16(a[0], a[1]); w.y = cvt_pk_bf16(a[2], a[3]); w.z = cvt_pk_bf16(b[0], b[1]); w.w = cvt_pk_bf16(b[2], b[3]); return w; }
; template <class Epi, class Sched, bool ALIGN_EPI = false, bool SP2 = false>
; __device__ __forceinline__ void gemm_phase(PG8_LAS unsigned char* lds, const Gemm g, const Sched& S, const Epi& E) {
;     ...
;         if (!has_next) break;
; #pragma unroll
;         for (int a = 0; a < 2; ++a)
; #pragma unroll
;             for (int b = 0; b < 2; ++b)
; #pragma unroll
;                 for (int m = 0; m < 4; ++m)
; #pragma unroll
;                     for (int n = 0; n < 2; ++n) acc[a][b][m][n] = (f32x4){0.f, 0.f, 0.f, 0.f};
;         cur = nxt; cA = nA; cB = nB; ++ui;
;         if constexpr (ALIGN_EPI) { if (wr == 1) PG8_BAR; }
;     __device__ __forceinline__ void operator()(const f32x4 (&acc)[2][2][4][2], const pg8::Unit& u, int wr, int wc, int fr, int fq) const {
;     ...
;             for (int m = 0; m < 4; ++m) { const float iq = (127.f / QCLIP) * rsqrtf(q1v[m] * (1.f / DM) + EPS);
; #pragma unroll
;                 for (int bj = 0; bj < 2; ++bj) { float hv[8]; unpack8(hr[m][bj], hv); const size_t off = (size_t)(row0 + ai * 128 + m * 16) * DM + col0 + bj * 128;
;                     f32x4 h0 = acc[ai][bj][m][0], h1 = acc[ai][bj][m][1];
; #pragma unroll
;                     for (int e = 0; e < 4; ++e) { h0[e] += hv[e]; h1[e] += hv[4 + e]; }
;                     *(u32x4*)(HB + off) = pack8(h0, h1);
;                     f32x4 q0, q1;
; #pragma unroll
;                     for (int ee = 0; ee < 4; ++ee) { q0[ee] = fminf(fmaxf(rintf(h0[ee] * iq), -127.f), 127.f); q1[ee] = fminf(fmaxf(rintf(h1[ee] * iq), -127.f), 127.f); }
;                     *(u32x2*)(HQ + off) = pack8_i8(q0, q1); } }
;             asm volatile("" ::: "memory"); }
	v_fmamk_f32 v22, v94, 0x39800000, v185
	v_cvt_i32_f32_sdwa v21, v23 dst_sel:WORD_1 dst_unused:UNUSED_PAD src0_sel:DWORD
	v_mul_f32_e32 v23, 0x4b800000, v22
	v_cmp_gt_f32_e32 vcc, s49, v22
	v_lshlrev_b32_e32 v20, 8, v20
	v_and_b32_e32 v20, 0xff00, v20
	v_cndmask_b32_e32 v22, v22, v23, vcc
	v_rsq_f32_e32 v22, v22
	v_and_b32_e32 v21, 0xff0000, v21
	v_or3_b32 v19, v19, v20, v21
	v_lshl_add_u64 v[20:21], s[16:17], 0, v[34:35]
	global_store_dwordx2 v[20:21], v[18:19], off
	v_mul_f32_e32 v18, 0x45800000, v22
	v_cndmask_b32_e32 v18, v22, v18, vcc
	s_waitcnt vmcnt(13)
	v_lshlrev_b32_e32 v21, 16, v70
	v_and_b32_e32 v22, 0xffff0000, v70
	v_lshlrev_b32_e32 v23, 16, v71
	v_and_b32_e32 v24, 0xffff0000, v71
	v_lshlrev_b32_e32 v25, 16, v72
	v_and_b32_e32 v26, 0xffff0000, v72
	v_lshlrev_b32_e32 v27, 16, v73
	v_mul_f32_e32 v20, 0x41e1c71c, v18
	v_and_b32_e32 v28, 0xffff0000, v73
	v_add_f32_e32 v14, v14, v21
	v_add_f32_e32 v21, v10, v25
	v_add_f32_e32 v15, v15, v22
	v_add_f32_e32 v22, v11, v26
	v_add_f32_e32 v16, v16, v23
	v_add_f32_e32 v23, v12, v27
	v_add_f32_e32 v17, v17, v24
	v_cvt_pk_bf16_f32 v10, v14, v15
	v_cvt_pk_bf16_f32 v11, v16, v17
	v_cvt_pk_bf16_f32 v12, v21, v22
	v_add_f32_e32 v24, v13, v28
	v_cvt_pk_bf16_f32 v13, v23, v24
	global_store_dwordx4 v[86:87], v[10:13], off
	v_lshlrev_b64 v[18:19], 12, v[88:89]
	v_lshl_add_u64 v[18:19], v[18:19], 0, v[162:163]
	v_mul_f32_e32 v12, v15, v20
	v_mul_f32_e32 v10, v14, v20
	v_rndne_f32_e32 v12, v12
	v_mul_f32_e32 v14, v16, v20
	v_mul_f32_e32 v16, v17, v20
	v_rndne_f32_e32 v10, v10
	v_med3_f32 v12, v12, s50, v186
	v_rndne_f32_e32 v14, v14
	v_rndne_f32_e32 v16, v16
	v_med3_f32 v10, v10, s50, v186
	v_med3_f32 v14, v14, s50, v186
	v_med3_f32 v16, v16, s50, v186
	v_cvt_i32_f32_e32 v12, v12
	v_cvt_i32_f32_e32 v10, v10
	v_cvt_i32_f32_sdwa v14, v14 dst_sel:WORD_1 dst_unused:UNUSED_PAD src0_sel:DWORD
	v_cvt_i32_f32_e32 v16, v16
	v_mul_f32_e32 v13, v22, v20
	v_mul_f32_e32 v11, v21, v20
	v_rndne_f32_e32 v13, v13
	v_mul_f32_e32 v15, v23, v20
	v_mul_f32_e32 v17, v24, v20
	v_lshlrev_b32_e32 v12, 8, v12
	v_rndne_f32_e32 v11, v11
	v_med3_f32 v13, v13, s50, v186
	v_rndne_f32_e32 v15, v15
	v_rndne_f32_e32 v17, v17
	v_and_b32_e32 v12, 0xff00, v12
	v_and_b32_e32 v14, 0xff0000, v14
	v_perm_b32 v10, v16, v10, s51
	v_med3_f32 v11, v11, s50, v186
	v_med3_f32 v15, v15, s50, v186
	v_med3_f32 v17, v17, s50, v186
	v_or3_b32 v10, v10, v12, v14
	v_cvt_i32_f32_e32 v12, v13
	v_cvt_i32_f32_e32 v11, v11
	v_cvt_i32_f32_sdwa v13, v15 dst_sel:WORD_1 dst_unused:UNUSED_PAD src0_sel:DWORD
	v_cvt_i32_f32_e32 v14, v17
	v_lshlrev_b32_e32 v12, 8, v12
	v_and_b32_e32 v12, 0xff00, v12
	v_and_b32_e32 v13, 0xff0000, v13
	v_perm_b32 v11, v14, v11, s51
	v_or3_b32 v11, v11, v12, v13
	v_lshl_add_u64 v[12:13], s[16:17], 0, v[18:19]
	global_store_dwordx2 v[12:13], v[10:11], off
	s_waitcnt vmcnt(14)
	v_lshlrev_b32_e32 v10, 16, v66
	v_and_b32_e32 v11, 0xffff0000, v66
	v_lshlrev_b32_e32 v12, 16, v67
	v_and_b32_e32 v13, 0xffff0000, v67
	v_lshlrev_b32_e32 v14, 16, v68
	v_and_b32_e32 v15, 0xffff0000, v68
	v_lshlrev_b32_e32 v16, 16, v69
	v_or_b32_e32 v18, 0x80, v18
	v_and_b32_e32 v17, 0xffff0000, v69
	v_add_f32_e32 v10, v6, v10
	v_add_f32_e32 v14, v2, v14
	v_add_f32_e32 v11, v7, v11
	v_add_f32_e32 v15, v3, v15
	v_add_f32_e32 v8, v8, v12
	v_add_f32_e32 v12, v4, v16
	v_add_f32_e32 v9, v9, v13
	v_cvt_pk_bf16_f32 v2, v10, v11
	v_cvt_pk_bf16_f32 v3, v8, v9
	v_cvt_pk_bf16_f32 v4, v14, v15
	v_lshl_add_u64 v[6:7], v[18:19], 1, s[14:15]
	v_add_f32_e32 v13, v5, v17
	v_cvt_pk_bf16_f32 v5, v12, v13
	global_store_dwordx4 v[6:7], v[2:5], off
	v_mul_f32_e32 v6, v8, v20
	v_mul_f32_e32 v8, v9, v20
	v_mul_f32_e32 v4, v11, v20
	v_mul_f32_e32 v2, v10, v20
	v_rndne_f32_e32 v4, v4
	v_rndne_f32_e32 v2, v2
	v_med3_f32 v4, v4, s50, v186
	v_rndne_f32_e32 v6, v6
	v_rndne_f32_e32 v8, v8
	v_med3_f32 v2, v2, s50, v186
	v_med3_f32 v6, v6, s50, v186
	v_med3_f32 v8, v8, s50, v186
	v_cvt_i32_f32_e32 v4, v4
	v_cvt_i32_f32_e32 v2, v2
	v_cvt_i32_f32_sdwa v6, v6 dst_sel:WORD_1 dst_unused:UNUSED_PAD src0_sel:DWORD
	v_cvt_i32_f32_e32 v8, v8
	v_mul_f32_e32 v5, v15, v20
	v_mul_f32_e32 v3, v14, v20
	v_rndne_f32_e32 v5, v5
	v_mul_f32_e32 v7, v12, v20
	v_mul_f32_e32 v9, v13, v20
	v_lshlrev_b32_e32 v4, 8, v4
	v_rndne_f32_e32 v3, v3
	v_med3_f32 v5, v5, s50, v186
	v_rndne_f32_e32 v7, v7
	v_rndne_f32_e32 v9, v9
	v_and_b32_e32 v4, 0xff00, v4
	v_and_b32_e32 v6, 0xff0000, v6
	v_perm_b32 v2, v8, v2, s51
	v_med3_f32 v3, v3, s50, v186
	v_med3_f32 v7, v7, s50, v186
	v_med3_f32 v9, v9, s50, v186
	v_or3_b32 v2, v2, v4, v6
	v_cvt_i32_f32_e32 v4, v5
	v_cvt_i32_f32_e32 v3, v3
	v_cvt_i32_f32_sdwa v5, v7 dst_sel:WORD_1 dst_unused:UNUSED_PAD src0_sel:DWORD
	v_cvt_i32_f32_e32 v6, v9
	v_lshlrev_b32_e32 v4, 8, v4
	v_and_b32_e32 v4, 0xff00, v4
	v_and_b32_e32 v5, 0xff0000, v5
	v_perm_b32 v3, v6, v3, s51
	v_or3_b32 v3, v3, v4, v5
	v_lshl_add_u64 v[4:5], s[16:17], 0, v[18:19]
	global_store_dwordx2 v[4:5], v[2:3], off
	s_and_b64 vcc, exec, s[6:7]
	s_mov_b64 s[6:7], -1
	s_cbranch_vccnz .LBB0_1364
	s_andn2_b64 vcc, exec, s[12:13]
	s_cbranch_vccnz .LBB0_1363
	s_barrier
	s_branch .LBB0_1363

; __device__ __forceinline__ f32x4 acc_i2f(const f32x4 a) { return __builtin_convertvector(__builtin_bit_cast(i32x4, a), f32x4); }
;     __device__ __forceinline__ void operator()(const f32x4 (&acc)[2][2][4][2], const pg8::Unit& u, int wr, int wc, int fr, int fq) const {
;         const int row0 = u.pm * 256 + wr * 64 + fr, col0 = u.pn * 256 + wc * 32 + 8 * fq;
;         f32x4 bv[2][2], sb[2][2];
; #pragma unroll
;         for (int bj = 0; bj < 2; ++bj) { bv[bj][0] = *(const f32x4*)(bg + col0 + bj * 128); bv[bj][1] = *(const f32x4*)(bg + col0 + bj * 128 + 4);
;             sb[bj][0] = *(const f32x4*)(cmax + col0 + bj * 128) * (1.f / 127.f); sb[bj][1] = *(const f32x4*)(cmax + col0 + bj * 128 + 4) * (1.f / 127.f); }
; #pragma unroll
;         for (int ai = 0; ai < 2; ++ai)
; #pragma unroll
;             for (int mp = 0; mp < 2; ++mp) {
;                 u32x4 hr[2][2], pr[2][2]; float q1v[2];
; #pragma unroll
;                 for (int mm = 0; mm < 2; ++mm) { const int row = row0 + ai * 128 + (2 * mp + mm) * 16; q1v[mm] = rss1[row];
; #pragma unroll
;                     for (int bj = 0; bj < 2; ++bj) { const size_t off = (size_t)row * DM + col0 + bj * 128; hr[mm][bj] = *(const u32x4*)(HB + off); pr[mm][bj] = *(const u32x4*)(PP + off); } }
; #pragma unroll
;                 for (int mm = 0; mm < 2; ++mm) { const int m = 2 * mp + mm, row = row0 + ai * 128 + m * 16; f32x4 ssv = {0.f, 0.f, 0.f, 0.f}; const float sa = (QCLIP / 127.f) * sqrtf(q1v[mm] * (1.f / DM) + EPS);
; #pragma unroll
;                     for (int bj = 0; bj < 2; ++bj) { const size_t off = (size_t)row * DM + col0 + bj * 128;
;                         f32x4 p0, p1, x0, x1; unpack8v(pr[mm][bj], p0, p1); unpack8v(hr[mm][bj], x0, x1);
;                         const f32x4 g0 = acc_i2f(acc[ai][bj][m][0]) * (sb[bj][0] * sa) + bv[bj][0], g1 = acc_i2f(acc[ai][bj][m][1]) * (sb[bj][1] * sa) + bv[bj][1];
;                         const f32x4 h0 = x0 + p0 * sigm4(g0), h1 = x1 + p1 * sigm4(g1);
;                         *(f32x4*)(H + off) = h0; *(f32x4*)(H + off + 4) = h1;
;                         ssv = ssv + h0 * h0; ssv = ssv + h1 * h1; }
.LBB0_1460:
	s_cmpk_lg_i32 s74, 0x100
	s_cbranch_scc1 .Lp8_orig_epi
	s_mov_b32 s98, s10
	s_mov_b32 s99, s46
	v_lshlrev_b32_e32 v54, 2, v1
	v_lshlrev_b32_e32 v55, 2, v199
	v_lshlrev_b32_e32 v56, 13, v1
	v_lshlrev_b32_e32 v57, 14, v1
	v_lshl_add_u32 v56, v199, 1, v56
	v_lshl_add_u32 v57, v199, 2, v57
	v_xor_b32_e32 v58, 16, v203
	v_xor_b32_e32 v59, 32, v203
	v_lshlrev_b32_e32 v58, 2, v58
	v_lshlrev_b32_e32 v59, 2, v59
	s_lshl_b32 s48, s99, 10
	s_add_u32 s50, s14, s48
	s_addc_u32 s51, s15, 0
	s_add_u32 s52, s18, s48
	s_addc_u32 s53, s19, 0
	s_lshl_b32 s49, s98, 10
	s_add_u32 s68, s28, s49
	s_addc_u32 s69, s29, 0
	s_add_u32 s70, s26, s49
	s_addc_u32 s71, s27, 0
	s_lshl_b32 s72, s98, 21
	s_lshl_b32 s73, s99, 9
	s_add_u32 s72, s72, s73
	s_add_u32 s86, s22, s72
	s_addc_u32 s87, s23, 0
	s_add_u32 s88, s24, s72
	s_addc_u32 s89, s25, 0
	s_lshl_b32 s72, s98, 22
	s_add_u32 s72, s72, s48
	s_add_u32 s84, s12, s72
	s_addc_u32 s85, s13, 0
	global_load_dwordx4 v[222:225], v55, s[50:51]
	global_load_dwordx4 v[226:229], v55, s[50:51] offset:16
	global_load_dwordx4 v[230:233], v55, s[50:51] offset:512
	global_load_dwordx4 v[234:237], v55, s[50:51] offset:528
	global_load_dwordx4 v[206:209], v55, s[52:53]
	global_load_dwordx4 v[210:213], v55, s[52:53] offset:16
	global_load_dwordx4 v[214:217], v55, s[52:53] offset:512
	global_load_dwordx4 v[218:221], v55, s[52:53] offset:528
	global_load_dword v66, v54, s[68:69]
	global_load_dwordx4 v[238:241], v56, s[86:87] nt
	global_load_dwordx4 v[242:245], v56, s[86:87] offset:256 nt
	global_load_dwordx4 v[246:249], v56, s[88:89] nt
	global_load_dwordx4 v[250:253], v56, s[88:89] offset:256 nt
	s_add_u32 s86, s86, 0x20000
	s_addc_u32 s87, s87, 0
	s_add_u32 s88, s88, 0x20000
	s_addc_u32 s89, s89, 0
	global_load_dword v67, v54, s[68:69] offset:64
	global_load_dwordx4 v[170:173], v56, s[86:87] nt
	global_load_dwordx4 v[174:177], v56, s[86:87] offset:256 nt
	global_load_dwordx4 v[178:181], v56, s[88:89] nt
	global_load_dwordx4 v[182:185], v56, s[88:89] offset:256 nt
	s_add_u32 s86, s86, 0x20000
	s_addc_u32 s87, s87, 0
	s_add_u32 s88, s88, 0x20000
	s_addc_u32 s89, s89, 0
	s_waitcnt vmcnt(5)
	v_pk_mul_f32 v[222:223], v[222:223], s[36:37] op_sel_hi:[1,0]
	v_pk_mul_f32 v[224:225], v[224:225], s[36:37] op_sel_hi:[1,0]
	v_pk_mul_f32 v[226:227], v[226:227], s[36:37] op_sel_hi:[1,0]
	v_pk_mul_f32 v[228:229], v[228:229], s[36:37] op_sel_hi:[1,0]
	v_pk_mul_f32 v[230:231], v[230:231], s[36:37] op_sel_hi:[1,0]
	v_pk_mul_f32 v[232:233], v[232:233], s[36:37] op_sel_hi:[1,0]
	v_pk_mul_f32 v[234:235], v[234:235], s[36:37] op_sel_hi:[1,0]
	v_pk_mul_f32 v[236:237], v[236:237], s[36:37] op_sel_hi:[1,0]
	v_fmamk_f32 v186, v66, 0x39800000, v204
	v_mul_f32_e32 v187, 0x4f800000, v186
	v_cmp_gt_f32_e32 vcc, s67, v186
	s_nop 1
	v_cndmask_b32_e32 v186, v186, v187, vcc
	v_sqrt_f32_e32 v190, v186
	s_nop 0
	v_add_u32_e32 v191, -1, v190
	v_add_u32_e32 v192, 1, v190
	v_fma_f32 v193, -v191, v190, v186
	v_fma_f32 v187, -v192, v190, v186
	v_cmp_ge_f32_e64 s[10:11], 0, v193
	s_nop 1
	v_cndmask_b32_e64 v190, v190, v191, s[10:11]
	v_cmp_lt_f32_e64 s[10:11], 0, v187
	s_nop 1
	v_cndmask_b32_e64 v190, v190, v192, s[10:11]
	v_mul_f32_e32 v191, 0x37800000, v190
	v_cndmask_b32_e32 v190, v190, v191, vcc
	v_cmp_class_f32_e32 vcc, v186, v205
	s_nop 1
	v_cndmask_b32_e32 v186, v190, v186, vcc
	v_mul_f32_e32 v188, 0x3d112245, v186
	v_cvt_f32_i32_e32 v50, v50
	v_cvt_f32_i32_e32 v51, v51
	v_cvt_f32_i32_e32 v52, v52
	v_cvt_f32_i32_e32 v53, v53
	v_pk_mul_f32 v[142:143], v[222:223], v[188:189] op_sel_hi:[1,0]
	v_pk_mul_f32 v[144:145], v[224:225], v[188:189] op_sel_hi:[1,0]
	v_pk_fma_f32 v[154:155], v[142:143], v[50:51], v[206:207]
	v_pk_fma_f32 v[156:157], v[144:145], v[52:53], v[208:209]
	v_mul_f32_e32 v154, 0xbfb8aa3b, v154
	v_mul_f32_e32 v155, 0xbfb8aa3b, v155
	v_mul_f32_e32 v156, 0xbfb8aa3b, v156
	v_mul_f32_e32 v157, 0xbfb8aa3b, v157
	v_exp_f32_e32 v154, v154
	v_exp_f32_e32 v155, v155
	v_exp_f32_e32 v156, v156
	v_exp_f32_e32 v157, v157
	v_lshlrev_b32_e32 v146, 16, v238
	v_and_b32_e32 v147, 0xffff0000, v238
	v_lshlrev_b32_e32 v148, 16, v239
	v_and_b32_e32 v149, 0xffff0000, v239
	v_add_f32_e32 v154, 1.0, v154
	v_add_f32_e32 v155, 1.0, v155
	v_add_f32_e32 v156, 1.0, v156
	v_add_f32_e32 v157, 1.0, v157
	v_rcp_f32_e32 v154, v154
	v_rcp_f32_e32 v155, v155
	v_rcp_f32_e32 v156, v156
	v_rcp_f32_e32 v157, v157
	v_lshlrev_b32_e32 v150, 16, v246
	v_and_b32_e32 v151, 0xffff0000, v246
	v_lshlrev_b32_e32 v152, 16, v247
	v_and_b32_e32 v153, 0xffff0000, v247
	v_pk_fma_f32 v[50:51], v[154:155], v[150:151], v[146:147]
	v_pk_fma_f32 v[52:53], v[156:157], v[152:153], v[148:149]
	v_pk_mul_f32 v[194:195], v[50:51], v[50:51]
	v_pk_mul_f32 v[196:197], v[52:53], v[52:53]
	v_cvt_f32_i32_e32 v138, v138
	v_cvt_f32_i32_e32 v139, v139
	v_cvt_f32_i32_e32 v140, v140
	v_cvt_f32_i32_e32 v141, v141
	v_pk_mul_f32 v[142:143], v[226:227], v[188:189] op_sel_hi:[1,0]
	v_pk_mul_f32 v[144:145], v[228:229], v[188:189] op_sel_hi:[1,0]
	v_pk_fma_f32 v[154:155], v[142:143], v[138:139], v[210:211]
	v_pk_fma_f32 v[156:157], v[144:145], v[140:141], v[212:213]
	v_mul_f32_e32 v154, 0xbfb8aa3b, v154
	v_mul_f32_e32 v155, 0xbfb8aa3b, v155
	v_mul_f32_e32 v156, 0xbfb8aa3b, v156
	v_mul_f32_e32 v157, 0xbfb8aa3b, v157
	v_exp_f32_e32 v154, v154
	v_exp_f32_e32 v155, v155
	v_exp_f32_e32 v156, v156
	v_exp_f32_e32 v157, v157
	v_lshlrev_b32_e32 v146, 16, v240
	v_and_b32_e32 v147, 0xffff0000, v240
	v_lshlrev_b32_e32 v148, 16, v241
	v_and_b32_e32 v149, 0xffff0000, v241
	v_add_f32_e32 v154, 1.0, v154
	v_add_f32_e32 v155, 1.0, v155
	v_add_f32_e32 v156, 1.0, v156
	v_add_f32_e32 v157, 1.0, v157
	v_rcp_f32_e32 v154, v154
	v_rcp_f32_e32 v155, v155
; __device__ __forceinline__ f32x4 acc_i2f(const f32x4 a) { return __builtin_convertvector(__builtin_bit_cast(i32x4, a), f32x4); }
;     __device__ __forceinline__ void operator()(const f32x4 (&acc)[2][2][4][2], const pg8::Unit& u, int wr, int wc, int fr, int fq) const {
;     ...
;                 for (int mm = 0; mm < 2; ++mm) { const int m = 2 * mp + mm, row = row0 + ai * 128 + m * 16; f32x4 ssv = {0.f, 0.f, 0.f, 0.f}; const float sa = (QCLIP / 127.f) * sqrtf(q1v[mm] * (1.f / DM) + EPS);
; #pragma unroll
;                     for (int bj = 0; bj < 2; ++bj) { const size_t off = (size_t)row * DM + col0 + bj * 128;
;                         f32x4 p0, p1, x0, x1; unpack8v(pr[mm][bj], p0, p1); unpack8v(hr[mm][bj], x0, x1);
;                         const f32x4 g0 = acc_i2f(acc[ai][bj][m][0]) * (sb[bj][0] * sa) + bv[bj][0], g1 = acc_i2f(acc[ai][bj][m][1]) * (sb[bj][1] * sa) + bv[bj][1];
;                         const f32x4 h0 = x0 + p0 * sigm4(g0), h1 = x1 + p1 * sigm4(g1);
;                         *(f32x4*)(H + off) = h0; *(f32x4*)(H + off + 4) = h1;
;                         ssv = ssv + h0 * h0; ssv = ssv + h1 * h1; }
;                     float ss = (ssv[0] + ssv[1]) + (ssv[2] + ssv[3]);
;                     ss += __shfl_xor(ss, 16); ss += __shfl_xor(ss, 32);
;                     if (fq == 0) unsafeAtomicAdd(rss3 + row, ss); }
	v_rcp_f32_e32 v156, v156
	v_rcp_f32_e32 v157, v157
	v_lshlrev_b32_e32 v150, 16, v248
	v_and_b32_e32 v151, 0xffff0000, v248
	v_lshlrev_b32_e32 v152, 16, v249
	v_and_b32_e32 v153, 0xffff0000, v249
	v_pk_fma_f32 v[138:139], v[154:155], v[150:151], v[146:147]
	v_pk_fma_f32 v[140:141], v[156:157], v[152:153], v[148:149]
	v_pk_fma_f32 v[194:195], v[138:139], v[138:139], v[194:195]
	v_pk_fma_f32 v[196:197], v[140:141], v[140:141], v[196:197]
	v_cvt_f32_i32_e32 v134, v134
	v_cvt_f32_i32_e32 v135, v135
	v_cvt_f32_i32_e32 v136, v136
	v_cvt_f32_i32_e32 v137, v137
	v_pk_mul_f32 v[142:143], v[230:231], v[188:189] op_sel_hi:[1,0]
	v_pk_mul_f32 v[144:145], v[232:233], v[188:189] op_sel_hi:[1,0]
	v_pk_fma_f32 v[154:155], v[142:143], v[134:135], v[214:215]
	v_pk_fma_f32 v[156:157], v[144:145], v[136:137], v[216:217]
	v_mul_f32_e32 v154, 0xbfb8aa3b, v154
	v_mul_f32_e32 v155, 0xbfb8aa3b, v155
	v_mul_f32_e32 v156, 0xbfb8aa3b, v156
	v_mul_f32_e32 v157, 0xbfb8aa3b, v157
	v_exp_f32_e32 v154, v154
	v_exp_f32_e32 v155, v155
	v_exp_f32_e32 v156, v156
	v_exp_f32_e32 v157, v157
	v_lshlrev_b32_e32 v146, 16, v242
	v_and_b32_e32 v147, 0xffff0000, v242
	v_lshlrev_b32_e32 v148, 16, v243
	v_and_b32_e32 v149, 0xffff0000, v243
	v_add_f32_e32 v154, 1.0, v154
	v_add_f32_e32 v155, 1.0, v155
	v_add_f32_e32 v156, 1.0, v156
	v_add_f32_e32 v157, 1.0, v157
	v_rcp_f32_e32 v154, v154
	v_rcp_f32_e32 v155, v155
	v_rcp_f32_e32 v156, v156
	v_rcp_f32_e32 v157, v157
	v_lshlrev_b32_e32 v150, 16, v250
	v_and_b32_e32 v151, 0xffff0000, v250
	v_lshlrev_b32_e32 v152, 16, v251
	v_and_b32_e32 v153, 0xffff0000, v251
	v_pk_fma_f32 v[134:135], v[154:155], v[150:151], v[146:147]
	v_pk_fma_f32 v[136:137], v[156:157], v[152:153], v[148:149]
	v_pk_fma_f32 v[194:195], v[134:135], v[134:135], v[194:195]
	v_pk_fma_f32 v[196:197], v[136:137], v[136:137], v[196:197]
	v_cvt_f32_i32_e32 v130, v130
	v_cvt_f32_i32_e32 v131, v131
	v_cvt_f32_i32_e32 v132, v132
	v_cvt_f32_i32_e32 v133, v133
	v_pk_mul_f32 v[142:143], v[234:235], v[188:189] op_sel_hi:[1,0]
	v_pk_mul_f32 v[144:145], v[236:237], v[188:189] op_sel_hi:[1,0]
	v_pk_fma_f32 v[154:155], v[142:143], v[130:131], v[218:219]
	v_pk_fma_f32 v[156:157], v[144:145], v[132:133], v[220:221]
	v_mul_f32_e32 v154, 0xbfb8aa3b, v154
	v_mul_f32_e32 v155, 0xbfb8aa3b, v155
	v_mul_f32_e32 v156, 0xbfb8aa3b, v156
	v_mul_f32_e32 v157, 0xbfb8aa3b, v157
	v_exp_f32_e32 v154, v154
	v_exp_f32_e32 v155, v155
	v_exp_f32_e32 v156, v156
	v_exp_f32_e32 v157, v157
	v_lshlrev_b32_e32 v146, 16, v244
	v_and_b32_e32 v147, 0xffff0000, v244
	v_lshlrev_b32_e32 v148, 16, v245
	v_and_b32_e32 v149, 0xffff0000, v245
	v_add_f32_e32 v154, 1.0, v154
	v_add_f32_e32 v155, 1.0, v155
	v_add_f32_e32 v156, 1.0, v156
	v_add_f32_e32 v157, 1.0, v157
	v_rcp_f32_e32 v154, v154
	v_rcp_f32_e32 v155, v155
	v_rcp_f32_e32 v156, v156
	v_rcp_f32_e32 v157, v157
	v_lshlrev_b32_e32 v150, 16, v252
	v_and_b32_e32 v151, 0xffff0000, v252
	v_lshlrev_b32_e32 v152, 16, v253
	v_and_b32_e32 v153, 0xffff0000, v253
	v_pk_fma_f32 v[130:131], v[154:155], v[150:151], v[146:147]
	v_pk_fma_f32 v[132:133], v[156:157], v[152:153], v[148:149]
	v_pk_fma_f32 v[194:195], v[130:131], v[130:131], v[194:195]
	v_pk_fma_f32 v[196:197], v[132:133], v[132:133], v[196:197]
	v_add_f32_e32 v194, v194, v195
	v_add_f32_e32 v196, v196, v197
	v_add_f32_e32 v194, v194, v196
	ds_bpermute_b32 v195, v58, v194
	s_waitcnt lgkmcnt(0)
	v_add_f32_e32 v194, v194, v195
	ds_bpermute_b32 v195, v59, v194
	s_waitcnt lgkmcnt(0)
	v_add_f32_e32 v194, v194, v195
	s_and_saveexec_b64 s[32:33], s[6:7]
	global_atomic_add_f32 v54, v194, s[70:71]
	s_or_b64 exec, exec, s[32:33]
	global_load_dword v66, v54, s[68:69] offset:128
	global_load_dwordx4 v[238:241], v56, s[86:87] nt
	global_load_dwordx4 v[242:245], v56, s[86:87] offset:256 nt
	global_load_dwordx4 v[246:249], v56, s[88:89] nt
	global_load_dwordx4 v[250:253], v56, s[88:89] offset:256 nt
	s_add_u32 s86, s86, 0x20000
	s_addc_u32 s87, s87, 0
	s_add_u32 s88, s88, 0x20000
	s_addc_u32 s89, s89, 0
	s_waitcnt vmcnt(6)
	v_fmamk_f32 v186, v67, 0x39800000, v204
	v_mul_f32_e32 v187, 0x4f800000, v186
	v_cmp_gt_f32_e32 vcc, s67, v186
	s_nop 1
	v_cndmask_b32_e32 v186, v186, v187, vcc
	v_sqrt_f32_e32 v190, v186
	s_nop 0
	v_add_u32_e32 v191, -1, v190
	v_add_u32_e32 v192, 1, v190
	v_fma_f32 v193, -v191, v190, v186
	v_fma_f32 v187, -v192, v190, v186
	v_cmp_ge_f32_e64 s[10:11], 0, v193
	s_nop 1
	v_cndmask_b32_e64 v190, v190, v191, s[10:11]
	v_cmp_lt_f32_e64 s[10:11], 0, v187
	s_nop 1
	v_cndmask_b32_e64 v190, v190, v192, s[10:11]
	v_mul_f32_e32 v191, 0x37800000, v190
	v_cndmask_b32_e32 v190, v190, v191, vcc
	v_cmp_class_f32_e32 vcc, v186, v205
	s_nop 1
	v_cndmask_b32_e32 v186, v190, v186, vcc
	v_mul_f32_e32 v188, 0x3d112245, v186
	v_cvt_f32_i32_e32 v126, v126
	v_cvt_f32_i32_e32 v127, v127
	v_cvt_f32_i32_e32 v128, v128
	v_cvt_f32_i32_e32 v129, v129
	v_pk_mul_f32 v[142:143], v[222:223], v[188:189] op_sel_hi:[1,0]
	v_pk_mul_f32 v[144:145], v[224:225], v[188:189] op_sel_hi:[1,0]
	v_pk_fma_f32 v[154:155], v[142:143], v[126:127], v[206:207]
	v_pk_fma_f32 v[156:157], v[144:145], v[128:129], v[208:209]
	v_mul_f32_e32 v154, 0xbfb8aa3b, v154
	v_mul_f32_e32 v155, 0xbfb8aa3b, v155
	v_mul_f32_e32 v156, 0xbfb8aa3b, v156
	v_mul_f32_e32 v157, 0xbfb8aa3b, v157
	v_exp_f32_e32 v154, v154
	v_exp_f32_e32 v155, v155
	v_exp_f32_e32 v156, v156
	v_exp_f32_e32 v157, v157
	v_lshlrev_b32_e32 v146, 16, v170
	v_and_b32_e32 v147, 0xffff0000, v170
	v_lshlrev_b32_e32 v148, 16, v171
	v_and_b32_e32 v149, 0xffff0000, v171
	v_add_f32_e32 v154, 1.0, v154
	v_add_f32_e32 v155, 1.0, v155
	v_add_f32_e32 v156, 1.0, v156
	v_add_f32_e32 v157, 1.0, v157
	v_rcp_f32_e32 v154, v154
; __device__ __forceinline__ f32x4 acc_i2f(const f32x4 a) { return __builtin_convertvector(__builtin_bit_cast(i32x4, a), f32x4); }
;     __device__ __forceinline__ void operator()(const f32x4 (&acc)[2][2][4][2], const pg8::Unit& u, int wr, int wc, int fr, int fq) const {
;     ...
;                 for (int mm = 0; mm < 2; ++mm) { const int m = 2 * mp + mm, row = row0 + ai * 128 + m * 16; f32x4 ssv = {0.f, 0.f, 0.f, 0.f}; const float sa = (QCLIP / 127.f) * sqrtf(q1v[mm] * (1.f / DM) + EPS);
; #pragma unroll
;                     for (int bj = 0; bj < 2; ++bj) { const size_t off = (size_t)row * DM + col0 + bj * 128;
;                         f32x4 p0, p1, x0, x1; unpack8v(pr[mm][bj], p0, p1); unpack8v(hr[mm][bj], x0, x1);
;                         const f32x4 g0 = acc_i2f(acc[ai][bj][m][0]) * (sb[bj][0] * sa) + bv[bj][0], g1 = acc_i2f(acc[ai][bj][m][1]) * (sb[bj][1] * sa) + bv[bj][1];
;                         const f32x4 h0 = x0 + p0 * sigm4(g0), h1 = x1 + p1 * sigm4(g1);
;                         *(f32x4*)(H + off) = h0; *(f32x4*)(H + off + 4) = h1;
;                         ssv = ssv + h0 * h0; ssv = ssv + h1 * h1; }
;                     float ss = (ssv[0] + ssv[1]) + (ssv[2] + ssv[3]);
;                     ss += __shfl_xor(ss, 16); ss += __shfl_xor(ss, 32);
;                     if (fq == 0) unsafeAtomicAdd(rss3 + row, ss); }
	v_rcp_f32_e32 v155, v155
	v_rcp_f32_e32 v156, v156
	v_rcp_f32_e32 v157, v157
	v_lshlrev_b32_e32 v150, 16, v178
	v_and_b32_e32 v151, 0xffff0000, v178
	v_lshlrev_b32_e32 v152, 16, v179
	v_and_b32_e32 v153, 0xffff0000, v179
	v_pk_fma_f32 v[126:127], v[154:155], v[150:151], v[146:147]
	v_pk_fma_f32 v[128:129], v[156:157], v[152:153], v[148:149]
	v_pk_mul_f32 v[194:195], v[126:127], v[126:127]
	v_pk_mul_f32 v[196:197], v[128:129], v[128:129]
	v_cvt_f32_i32_e32 v122, v122
	v_cvt_f32_i32_e32 v123, v123
	v_cvt_f32_i32_e32 v124, v124
	v_cvt_f32_i32_e32 v125, v125
	v_pk_mul_f32 v[142:143], v[226:227], v[188:189] op_sel_hi:[1,0]
	v_pk_mul_f32 v[144:145], v[228:229], v[188:189] op_sel_hi:[1,0]
	v_pk_fma_f32 v[154:155], v[142:143], v[122:123], v[210:211]
	v_pk_fma_f32 v[156:157], v[144:145], v[124:125], v[212:213]
	v_mul_f32_e32 v154, 0xbfb8aa3b, v154
	v_mul_f32_e32 v155, 0xbfb8aa3b, v155
	v_mul_f32_e32 v156, 0xbfb8aa3b, v156
	v_mul_f32_e32 v157, 0xbfb8aa3b, v157
	v_exp_f32_e32 v154, v154
	v_exp_f32_e32 v155, v155
	v_exp_f32_e32 v156, v156
	v_exp_f32_e32 v157, v157
	v_lshlrev_b32_e32 v146, 16, v172
	v_and_b32_e32 v147, 0xffff0000, v172
	v_lshlrev_b32_e32 v148, 16, v173
	v_and_b32_e32 v149, 0xffff0000, v173
	v_add_f32_e32 v154, 1.0, v154
	v_add_f32_e32 v155, 1.0, v155
	v_add_f32_e32 v156, 1.0, v156
	v_add_f32_e32 v157, 1.0, v157
	v_rcp_f32_e32 v154, v154
	v_rcp_f32_e32 v155, v155
	v_rcp_f32_e32 v156, v156
	v_rcp_f32_e32 v157, v157
	v_lshlrev_b32_e32 v150, 16, v180
	v_and_b32_e32 v151, 0xffff0000, v180
	v_lshlrev_b32_e32 v152, 16, v181
	v_and_b32_e32 v153, 0xffff0000, v181
	v_pk_fma_f32 v[122:123], v[154:155], v[150:151], v[146:147]
	v_pk_fma_f32 v[124:125], v[156:157], v[152:153], v[148:149]
	v_pk_fma_f32 v[194:195], v[122:123], v[122:123], v[194:195]
	v_pk_fma_f32 v[196:197], v[124:125], v[124:125], v[196:197]
	v_cvt_f32_i32_e32 v118, v118
	v_cvt_f32_i32_e32 v119, v119
	v_cvt_f32_i32_e32 v120, v120
	v_cvt_f32_i32_e32 v121, v121
	v_pk_mul_f32 v[142:143], v[230:231], v[188:189] op_sel_hi:[1,0]
	v_pk_mul_f32 v[144:145], v[232:233], v[188:189] op_sel_hi:[1,0]
	v_pk_fma_f32 v[154:155], v[142:143], v[118:119], v[214:215]
	v_pk_fma_f32 v[156:157], v[144:145], v[120:121], v[216:217]
	v_mul_f32_e32 v154, 0xbfb8aa3b, v154
	v_mul_f32_e32 v155, 0xbfb8aa3b, v155
	v_mul_f32_e32 v156, 0xbfb8aa3b, v156
	v_mul_f32_e32 v157, 0xbfb8aa3b, v157
	v_exp_f32_e32 v154, v154
	v_exp_f32_e32 v155, v155
	v_exp_f32_e32 v156, v156
	v_exp_f32_e32 v157, v157
	v_lshlrev_b32_e32 v146, 16, v174
	v_and_b32_e32 v147, 0xffff0000, v174
	v_lshlrev_b32_e32 v148, 16, v175
	v_and_b32_e32 v149, 0xffff0000, v175
	v_add_f32_e32 v154, 1.0, v154
	v_add_f32_e32 v155, 1.0, v155
	v_add_f32_e32 v156, 1.0, v156
	v_add_f32_e32 v157, 1.0, v157
	v_rcp_f32_e32 v154, v154
	v_rcp_f32_e32 v155, v155
	v_rcp_f32_e32 v156, v156
	v_rcp_f32_e32 v157, v157
	v_lshlrev_b32_e32 v150, 16, v182
	v_and_b32_e32 v151, 0xffff0000, v182
	v_lshlrev_b32_e32 v152, 16, v183
	v_and_b32_e32 v153, 0xffff0000, v183
	v_pk_fma_f32 v[118:119], v[154:155], v[150:151], v[146:147]
	v_pk_fma_f32 v[120:121], v[156:157], v[152:153], v[148:149]
	v_pk_fma_f32 v[194:195], v[118:119], v[118:119], v[194:195]
	v_pk_fma_f32 v[196:197], v[120:121], v[120:121], v[196:197]
	v_cvt_f32_i32_e32 v114, v114
	v_cvt_f32_i32_e32 v115, v115
	v_cvt_f32_i32_e32 v116, v116
	v_cvt_f32_i32_e32 v117, v117
	v_pk_mul_f32 v[142:143], v[234:235], v[188:189] op_sel_hi:[1,0]
	v_pk_mul_f32 v[144:145], v[236:237], v[188:189] op_sel_hi:[1,0]
	v_pk_fma_f32 v[154:155], v[142:143], v[114:115], v[218:219]
	v_pk_fma_f32 v[156:157], v[144:145], v[116:117], v[220:221]
	v_mul_f32_e32 v154, 0xbfb8aa3b, v154
	v_mul_f32_e32 v155, 0xbfb8aa3b, v155
	v_mul_f32_e32 v156, 0xbfb8aa3b, v156
	v_mul_f32_e32 v157, 0xbfb8aa3b, v157
	v_exp_f32_e32 v154, v154
	v_exp_f32_e32 v155, v155
	v_exp_f32_e32 v156, v156
	v_exp_f32_e32 v157, v157
	v_lshlrev_b32_e32 v146, 16, v176
	v_and_b32_e32 v147, 0xffff0000, v176
	v_lshlrev_b32_e32 v148, 16, v177
	v_and_b32_e32 v149, 0xffff0000, v177
	v_add_f32_e32 v154, 1.0, v154
	v_add_f32_e32 v155, 1.0, v155
	v_add_f32_e32 v156, 1.0, v156
	v_add_f32_e32 v157, 1.0, v157
	v_rcp_f32_e32 v154, v154
	v_rcp_f32_e32 v155, v155
	v_rcp_f32_e32 v156, v156
	v_rcp_f32_e32 v157, v157
	v_lshlrev_b32_e32 v150, 16, v184
	v_and_b32_e32 v151, 0xffff0000, v184
	v_lshlrev_b32_e32 v152, 16, v185
	v_and_b32_e32 v153, 0xffff0000, v185
	v_pk_fma_f32 v[114:115], v[154:155], v[150:151], v[146:147]
	v_pk_fma_f32 v[116:117], v[156:157], v[152:153], v[148:149]
	v_pk_fma_f32 v[194:195], v[114:115], v[114:115], v[194:195]
	v_pk_fma_f32 v[196:197], v[116:117], v[116:117], v[196:197]
	v_add_f32_e32 v194, v194, v195
	v_add_f32_e32 v196, v196, v197
	v_add_f32_e32 v194, v194, v196
	ds_bpermute_b32 v195, v58, v194
	s_waitcnt lgkmcnt(0)
	v_add_f32_e32 v194, v194, v195
	ds_bpermute_b32 v195, v59, v194
	s_waitcnt lgkmcnt(0)
	v_add_f32_e32 v194, v194, v195
	s_and_saveexec_b64 s[32:33], s[6:7]
	global_atomic_add_f32 v54, v194, s[70:71] offset:64
	s_or_b64 exec, exec, s[32:33]
	global_load_dword v67, v54, s[68:69] offset:192
	global_load_dwordx4 v[170:173], v56, s[86:87] nt
	global_load_dwordx4 v[174:177], v56, s[86:87] offset:256 nt
	global_load_dwordx4 v[178:181], v56, s[88:89] nt
	global_load_dwordx4 v[182:185], v56, s[88:89] offset:256 nt
	s_add_u32 s86, s86, 0xa0000
	s_addc_u32 s87, s87, 0
	s_add_u32 s88, s88, 0xa0000
	s_addc_u32 s89, s89, 0
	s_waitcnt vmcnt(6)
; __device__ __forceinline__ f32x4 acc_i2f(const f32x4 a) { return __builtin_convertvector(__builtin_bit_cast(i32x4, a), f32x4); }
;     __device__ __forceinline__ void operator()(const f32x4 (&acc)[2][2][4][2], const pg8::Unit& u, int wr, int wc, int fr, int fq) const {
;     ...
;                 for (int mm = 0; mm < 2; ++mm) { const int m = 2 * mp + mm, row = row0 + ai * 128 + m * 16; f32x4 ssv = {0.f, 0.f, 0.f, 0.f}; const float sa = (QCLIP / 127.f) * sqrtf(q1v[mm] * (1.f / DM) + EPS);
; #pragma unroll
;                     for (int bj = 0; bj < 2; ++bj) { const size_t off = (size_t)row * DM + col0 + bj * 128;
;                         f32x4 p0, p1, x0, x1; unpack8v(pr[mm][bj], p0, p1); unpack8v(hr[mm][bj], x0, x1);
;                         const f32x4 g0 = acc_i2f(acc[ai][bj][m][0]) * (sb[bj][0] * sa) + bv[bj][0], g1 = acc_i2f(acc[ai][bj][m][1]) * (sb[bj][1] * sa) + bv[bj][1];
;                         const f32x4 h0 = x0 + p0 * sigm4(g0), h1 = x1 + p1 * sigm4(g1);
;                         *(f32x4*)(H + off) = h0; *(f32x4*)(H + off + 4) = h1;
;                         ssv = ssv + h0 * h0; ssv = ssv + h1 * h1; }
;                     float ss = (ssv[0] + ssv[1]) + (ssv[2] + ssv[3]);
;                     ss += __shfl_xor(ss, 16); ss += __shfl_xor(ss, 32);
;                     if (fq == 0) unsafeAtomicAdd(rss3 + row, ss); }
	v_fmamk_f32 v186, v66, 0x39800000, v204
	v_mul_f32_e32 v187, 0x4f800000, v186
	v_cmp_gt_f32_e32 vcc, s67, v186
	s_nop 1
	v_cndmask_b32_e32 v186, v186, v187, vcc
	v_sqrt_f32_e32 v190, v186
	s_nop 0
	v_add_u32_e32 v191, -1, v190
	v_add_u32_e32 v192, 1, v190
	v_fma_f32 v193, -v191, v190, v186
	v_fma_f32 v187, -v192, v190, v186
	v_cmp_ge_f32_e64 s[10:11], 0, v193
	s_nop 1
	v_cndmask_b32_e64 v190, v190, v191, s[10:11]
	v_cmp_lt_f32_e64 s[10:11], 0, v187
	s_nop 1
	v_cndmask_b32_e64 v190, v190, v192, s[10:11]
	v_mul_f32_e32 v191, 0x37800000, v190
	v_cndmask_b32_e32 v190, v190, v191, vcc
	v_cmp_class_f32_e32 vcc, v186, v205
	s_nop 1
	v_cndmask_b32_e32 v186, v190, v186, vcc
	v_mul_f32_e32 v188, 0x3d112245, v186
	v_cvt_f32_i32_e32 v110, v110
	v_cvt_f32_i32_e32 v111, v111
	v_cvt_f32_i32_e32 v112, v112
	v_cvt_f32_i32_e32 v113, v113
	v_pk_mul_f32 v[142:143], v[222:223], v[188:189] op_sel_hi:[1,0]
	v_pk_mul_f32 v[144:145], v[224:225], v[188:189] op_sel_hi:[1,0]
	v_pk_fma_f32 v[154:155], v[142:143], v[110:111], v[206:207]
	v_pk_fma_f32 v[156:157], v[144:145], v[112:113], v[208:209]
	v_mul_f32_e32 v154, 0xbfb8aa3b, v154
	v_mul_f32_e32 v155, 0xbfb8aa3b, v155
	v_mul_f32_e32 v156, 0xbfb8aa3b, v156
	v_mul_f32_e32 v157, 0xbfb8aa3b, v157
	v_exp_f32_e32 v154, v154
	v_exp_f32_e32 v155, v155
	v_exp_f32_e32 v156, v156
	v_exp_f32_e32 v157, v157
	v_lshlrev_b32_e32 v146, 16, v238
	v_and_b32_e32 v147, 0xffff0000, v238
	v_lshlrev_b32_e32 v148, 16, v239
	v_and_b32_e32 v149, 0xffff0000, v239
	v_add_f32_e32 v154, 1.0, v154
	v_add_f32_e32 v155, 1.0, v155
	v_add_f32_e32 v156, 1.0, v156
	v_add_f32_e32 v157, 1.0, v157
	v_rcp_f32_e32 v154, v154
	v_rcp_f32_e32 v155, v155
	v_rcp_f32_e32 v156, v156
	v_rcp_f32_e32 v157, v157
	v_lshlrev_b32_e32 v150, 16, v246
	v_and_b32_e32 v151, 0xffff0000, v246
	v_lshlrev_b32_e32 v152, 16, v247
	v_and_b32_e32 v153, 0xffff0000, v247
	v_pk_fma_f32 v[110:111], v[154:155], v[150:151], v[146:147]
	v_pk_fma_f32 v[112:113], v[156:157], v[152:153], v[148:149]
	v_pk_mul_f32 v[194:195], v[110:111], v[110:111]
	v_pk_mul_f32 v[196:197], v[112:113], v[112:113]
	v_cvt_f32_i32_e32 v106, v106
	v_cvt_f32_i32_e32 v107, v107
	v_cvt_f32_i32_e32 v108, v108
	v_cvt_f32_i32_e32 v109, v109
	v_pk_mul_f32 v[142:143], v[226:227], v[188:189] op_sel_hi:[1,0]
	v_pk_mul_f32 v[144:145], v[228:229], v[188:189] op_sel_hi:[1,0]
	v_pk_fma_f32 v[154:155], v[142:143], v[106:107], v[210:211]
	v_pk_fma_f32 v[156:157], v[144:145], v[108:109], v[212:213]
	v_mul_f32_e32 v154, 0xbfb8aa3b, v154
	v_mul_f32_e32 v155, 0xbfb8aa3b, v155
	v_mul_f32_e32 v156, 0xbfb8aa3b, v156
	v_mul_f32_e32 v157, 0xbfb8aa3b, v157
	v_exp_f32_e32 v154, v154
	v_exp_f32_e32 v155, v155
	v_exp_f32_e32 v156, v156
	v_exp_f32_e32 v157, v157
	v_lshlrev_b32_e32 v146, 16, v240
	v_and_b32_e32 v147, 0xffff0000, v240
	v_lshlrev_b32_e32 v148, 16, v241
	v_and_b32_e32 v149, 0xffff0000, v241
	v_add_f32_e32 v154, 1.0, v154
	v_add_f32_e32 v155, 1.0, v155
	v_add_f32_e32 v156, 1.0, v156
	v_add_f32_e32 v157, 1.0, v157
	v_rcp_f32_e32 v154, v154
	v_rcp_f32_e32 v155, v155
	v_rcp_f32_e32 v156, v156
	v_rcp_f32_e32 v157, v157
	v_lshlrev_b32_e32 v150, 16, v248
	v_and_b32_e32 v151, 0xffff0000, v248
	v_lshlrev_b32_e32 v152, 16, v249
	v_and_b32_e32 v153, 0xffff0000, v249
	v_pk_fma_f32 v[106:107], v[154:155], v[150:151], v[146:147]
	v_pk_fma_f32 v[108:109], v[156:157], v[152:153], v[148:149]
	v_pk_fma_f32 v[194:195], v[106:107], v[106:107], v[194:195]
	v_pk_fma_f32 v[196:197], v[108:109], v[108:109], v[196:197]
	v_cvt_f32_i32_e32 v102, v102
	v_cvt_f32_i32_e32 v103, v103
	v_cvt_f32_i32_e32 v104, v104
	v_cvt_f32_i32_e32 v105, v105
	v_pk_mul_f32 v[142:143], v[230:231], v[188:189] op_sel_hi:[1,0]
	v_pk_mul_f32 v[144:145], v[232:233], v[188:189] op_sel_hi:[1,0]
	v_pk_fma_f32 v[154:155], v[142:143], v[102:103], v[214:215]
	v_pk_fma_f32 v[156:157], v[144:145], v[104:105], v[216:217]
	v_mul_f32_e32 v154, 0xbfb8aa3b, v154
	v_mul_f32_e32 v155, 0xbfb8aa3b, v155
	v_mul_f32_e32 v156, 0xbfb8aa3b, v156
	v_mul_f32_e32 v157, 0xbfb8aa3b, v157
	v_exp_f32_e32 v154, v154
	v_exp_f32_e32 v155, v155
	v_exp_f32_e32 v156, v156
	v_exp_f32_e32 v157, v157
	v_lshlrev_b32_e32 v146, 16, v242
	v_and_b32_e32 v147, 0xffff0000, v242
	v_lshlrev_b32_e32 v148, 16, v243
	v_and_b32_e32 v149, 0xffff0000, v243
	v_add_f32_e32 v154, 1.0, v154
	v_add_f32_e32 v155, 1.0, v155
	v_add_f32_e32 v156, 1.0, v156
	v_add_f32_e32 v157, 1.0, v157
	v_rcp_f32_e32 v154, v154
	v_rcp_f32_e32 v155, v155
	v_rcp_f32_e32 v156, v156
	v_rcp_f32_e32 v157, v157
	v_lshlrev_b32_e32 v150, 16, v250
	v_and_b32_e32 v151, 0xffff0000, v250
	v_lshlrev_b32_e32 v152, 16, v251
	v_and_b32_e32 v153, 0xffff0000, v251
	v_pk_fma_f32 v[102:103], v[154:155], v[150:151], v[146:147]
	v_pk_fma_f32 v[104:105], v[156:157], v[152:153], v[148:149]
	v_pk_fma_f32 v[194:195], v[102:103], v[102:103], v[194:195]
	v_pk_fma_f32 v[196:197], v[104:105], v[104:105], v[196:197]
	v_cvt_f32_i32_e32 v98, v98
	v_cvt_f32_i32_e32 v99, v99
	v_cvt_f32_i32_e32 v100, v100
	v_cvt_f32_i32_e32 v101, v101
	v_pk_mul_f32 v[142:143], v[234:235], v[188:189] op_sel_hi:[1,0]
	v_pk_mul_f32 v[144:145], v[236:237], v[188:189] op_sel_hi:[1,0]
	v_pk_fma_f32 v[154:155], v[142:143], v[98:99], v[218:219]
	v_pk_fma_f32 v[156:157], v[144:145], v[100:101], v[220:221]
	v_mul_f32_e32 v154, 0xbfb8aa3b, v154
	v_mul_f32_e32 v155, 0xbfb8aa3b, v155
	v_mul_f32_e32 v156, 0xbfb8aa3b, v156
	v_mul_f32_e32 v157, 0xbfb8aa3b, v157
	v_exp_f32_e32 v154, v154
	v_exp_f32_e32 v155, v155
	v_exp_f32_e32 v156, v156
	v_exp_f32_e32 v157, v157
	v_lshlrev_b32_e32 v146, 16, v244
	v_and_b32_e32 v147, 0xffff0000, v244
	v_lshlrev_b32_e32 v148, 16, v245
	v_and_b32_e32 v149, 0xffff0000, v245
	v_add_f32_e32 v154, 1.0, v154
	v_add_f32_e32 v155, 1.0, v155
	v_add_f32_e32 v156, 1.0, v156
	v_add_f32_e32 v157, 1.0, v157
	v_rcp_f32_e32 v154, v154
	v_rcp_f32_e32 v155, v155
	v_rcp_f32_e32 v156, v156
	v_rcp_f32_e32 v157, v157
	v_lshlrev_b32_e32 v150, 16, v252
	v_and_b32_e32 v151, 0xffff0000, v252
	v_lshlrev_b32_e32 v152, 16, v253
	v_and_b32_e32 v153, 0xffff0000, v253
	v_pk_fma_f32 v[98:99], v[154:155], v[150:151], v[146:147]
	v_pk_fma_f32 v[100:101], v[156:157], v[152:153], v[148:149]
	v_pk_fma_f32 v[194:195], v[98:99], v[98:99], v[194:195]
	v_pk_fma_f32 v[196:197], v[100:101], v[100:101], v[196:197]
	v_add_f32_e32 v194, v194, v195
	v_add_f32_e32 v196, v196, v197
	v_add_f32_e32 v194, v194, v196
	ds_bpermute_b32 v195, v58, v194
	s_waitcnt lgkmcnt(0)
; __device__ __forceinline__ f32x4 acc_i2f(const f32x4 a) { return __builtin_convertvector(__builtin_bit_cast(i32x4, a), f32x4); }
;     __device__ __forceinline__ void operator()(const f32x4 (&acc)[2][2][4][2], const pg8::Unit& u, int wr, int wc, int fr, int fq) const {
;     ...
;                 for (int mm = 0; mm < 2; ++mm) { const int m = 2 * mp + mm, row = row0 + ai * 128 + m * 16; f32x4 ssv = {0.f, 0.f, 0.f, 0.f}; const float sa = (QCLIP / 127.f) * sqrtf(q1v[mm] * (1.f / DM) + EPS);
; #pragma unroll
;                     for (int bj = 0; bj < 2; ++bj) { const size_t off = (size_t)row * DM + col0 + bj * 128;
;                         f32x4 p0, p1, x0, x1; unpack8v(pr[mm][bj], p0, p1); unpack8v(hr[mm][bj], x0, x1);
;                         const f32x4 g0 = acc_i2f(acc[ai][bj][m][0]) * (sb[bj][0] * sa) + bv[bj][0], g1 = acc_i2f(acc[ai][bj][m][1]) * (sb[bj][1] * sa) + bv[bj][1];
;                         const f32x4 h0 = x0 + p0 * sigm4(g0), h1 = x1 + p1 * sigm4(g1);
;                         *(f32x4*)(H + off) = h0; *(f32x4*)(H + off + 4) = h1;
;                         ssv = ssv + h0 * h0; ssv = ssv + h1 * h1; }
;                     float ss = (ssv[0] + ssv[1]) + (ssv[2] + ssv[3]);
;                     ss += __shfl_xor(ss, 16); ss += __shfl_xor(ss, 32);
;                     if (fq == 0) unsafeAtomicAdd(rss3 + row, ss); }
	v_add_f32_e32 v194, v194, v195
	ds_bpermute_b32 v195, v59, v194
	s_waitcnt lgkmcnt(0)
	v_add_f32_e32 v194, v194, v195
	s_and_saveexec_b64 s[32:33], s[6:7]
	global_atomic_add_f32 v54, v194, s[70:71] offset:128
	s_or_b64 exec, exec, s[32:33]
	global_load_dword v66, v54, s[68:69] offset:512
	global_load_dwordx4 v[238:241], v56, s[86:87] nt
	global_load_dwordx4 v[242:245], v56, s[86:87] offset:256 nt
	global_load_dwordx4 v[246:249], v56, s[88:89] nt
	global_load_dwordx4 v[250:253], v56, s[88:89] offset:256 nt
	s_add_u32 s86, s86, 0x20000
	s_addc_u32 s87, s87, 0
	s_add_u32 s88, s88, 0x20000
	s_addc_u32 s89, s89, 0
	s_waitcnt vmcnt(6)
	v_fmamk_f32 v186, v67, 0x39800000, v204
	v_mul_f32_e32 v187, 0x4f800000, v186
	v_cmp_gt_f32_e32 vcc, s67, v186
	s_nop 1
	v_cndmask_b32_e32 v186, v186, v187, vcc
	v_sqrt_f32_e32 v190, v186
	s_nop 0
	v_add_u32_e32 v191, -1, v190
	v_add_u32_e32 v192, 1, v190
	v_fma_f32 v193, -v191, v190, v186
	v_fma_f32 v187, -v192, v190, v186
	v_cmp_ge_f32_e64 s[10:11], 0, v193
	s_nop 1
	v_cndmask_b32_e64 v190, v190, v191, s[10:11]
	v_cmp_lt_f32_e64 s[10:11], 0, v187
	s_nop 1
	v_cndmask_b32_e64 v190, v190, v192, s[10:11]
	v_mul_f32_e32 v191, 0x37800000, v190
	v_cndmask_b32_e32 v190, v190, v191, vcc
	v_cmp_class_f32_e32 vcc, v186, v205
	s_nop 1
	v_cndmask_b32_e32 v186, v190, v186, vcc
	v_mul_f32_e32 v188, 0x3d112245, v186
	v_cvt_f32_i32_e32 v94, v94
	v_cvt_f32_i32_e32 v95, v95
	v_cvt_f32_i32_e32 v96, v96
	v_cvt_f32_i32_e32 v97, v97
	v_pk_mul_f32 v[142:143], v[222:223], v[188:189] op_sel_hi:[1,0]
	v_pk_mul_f32 v[144:145], v[224:225], v[188:189] op_sel_hi:[1,0]
	v_pk_fma_f32 v[154:155], v[142:143], v[94:95], v[206:207]
	v_pk_fma_f32 v[156:157], v[144:145], v[96:97], v[208:209]
	v_mul_f32_e32 v154, 0xbfb8aa3b, v154
	v_mul_f32_e32 v155, 0xbfb8aa3b, v155
	v_mul_f32_e32 v156, 0xbfb8aa3b, v156
	v_mul_f32_e32 v157, 0xbfb8aa3b, v157
	v_exp_f32_e32 v154, v154
	v_exp_f32_e32 v155, v155
	v_exp_f32_e32 v156, v156
	v_exp_f32_e32 v157, v157
	v_lshlrev_b32_e32 v146, 16, v170
	v_and_b32_e32 v147, 0xffff0000, v170
	v_lshlrev_b32_e32 v148, 16, v171
	v_and_b32_e32 v149, 0xffff0000, v171
	v_add_f32_e32 v154, 1.0, v154
	v_add_f32_e32 v155, 1.0, v155
	v_add_f32_e32 v156, 1.0, v156
	v_add_f32_e32 v157, 1.0, v157
	v_rcp_f32_e32 v154, v154
	v_rcp_f32_e32 v155, v155
	v_rcp_f32_e32 v156, v156
	v_rcp_f32_e32 v157, v157
	v_lshlrev_b32_e32 v150, 16, v178
	v_and_b32_e32 v151, 0xffff0000, v178
	v_lshlrev_b32_e32 v152, 16, v179
	v_and_b32_e32 v153, 0xffff0000, v179
	v_pk_fma_f32 v[94:95], v[154:155], v[150:151], v[146:147]
	v_pk_fma_f32 v[96:97], v[156:157], v[152:153], v[148:149]
	v_pk_mul_f32 v[194:195], v[94:95], v[94:95]
	v_pk_mul_f32 v[196:197], v[96:97], v[96:97]
	v_cvt_f32_i32_e32 v90, v90
	v_cvt_f32_i32_e32 v91, v91
	v_cvt_f32_i32_e32 v92, v92
	v_cvt_f32_i32_e32 v93, v93
	v_pk_mul_f32 v[142:143], v[226:227], v[188:189] op_sel_hi:[1,0]
	v_pk_mul_f32 v[144:145], v[228:229], v[188:189] op_sel_hi:[1,0]
	v_pk_fma_f32 v[154:155], v[142:143], v[90:91], v[210:211]
	v_pk_fma_f32 v[156:157], v[144:145], v[92:93], v[212:213]
	v_mul_f32_e32 v154, 0xbfb8aa3b, v154
	v_mul_f32_e32 v155, 0xbfb8aa3b, v155
	v_mul_f32_e32 v156, 0xbfb8aa3b, v156
	v_mul_f32_e32 v157, 0xbfb8aa3b, v157
	v_exp_f32_e32 v154, v154
	v_exp_f32_e32 v155, v155
	v_exp_f32_e32 v156, v156
	v_exp_f32_e32 v157, v157
	v_lshlrev_b32_e32 v146, 16, v172
	v_and_b32_e32 v147, 0xffff0000, v172
	v_lshlrev_b32_e32 v148, 16, v173
	v_and_b32_e32 v149, 0xffff0000, v173
	v_add_f32_e32 v154, 1.0, v154
	v_add_f32_e32 v155, 1.0, v155
	v_add_f32_e32 v156, 1.0, v156
	v_add_f32_e32 v157, 1.0, v157
	v_rcp_f32_e32 v154, v154
	v_rcp_f32_e32 v155, v155
	v_rcp_f32_e32 v156, v156
	v_rcp_f32_e32 v157, v157
	v_lshlrev_b32_e32 v150, 16, v180
	v_and_b32_e32 v151, 0xffff0000, v180
	v_lshlrev_b32_e32 v152, 16, v181
	v_and_b32_e32 v153, 0xffff0000, v181
	v_pk_fma_f32 v[90:91], v[154:155], v[150:151], v[146:147]
	v_pk_fma_f32 v[92:93], v[156:157], v[152:153], v[148:149]
	v_pk_fma_f32 v[194:195], v[90:91], v[90:91], v[194:195]
	v_pk_fma_f32 v[196:197], v[92:93], v[92:93], v[196:197]
	v_cvt_f32_i32_e32 v86, v86
	v_cvt_f32_i32_e32 v87, v87
	v_cvt_f32_i32_e32 v88, v88
	v_cvt_f32_i32_e32 v89, v89
	v_pk_mul_f32 v[142:143], v[230:231], v[188:189] op_sel_hi:[1,0]
	v_pk_mul_f32 v[144:145], v[232:233], v[188:189] op_sel_hi:[1,0]
	v_pk_fma_f32 v[154:155], v[142:143], v[86:87], v[214:215]
	v_pk_fma_f32 v[156:157], v[144:145], v[88:89], v[216:217]
	v_mul_f32_e32 v154, 0xbfb8aa3b, v154
	v_mul_f32_e32 v155, 0xbfb8aa3b, v155
	v_mul_f32_e32 v156, 0xbfb8aa3b, v156
	v_mul_f32_e32 v157, 0xbfb8aa3b, v157
	v_exp_f32_e32 v154, v154
	v_exp_f32_e32 v155, v155
	v_exp_f32_e32 v156, v156
	v_exp_f32_e32 v157, v157
	v_lshlrev_b32_e32 v146, 16, v174
	v_and_b32_e32 v147, 0xffff0000, v174
	v_lshlrev_b32_e32 v148, 16, v175
	v_and_b32_e32 v149, 0xffff0000, v175
	v_add_f32_e32 v154, 1.0, v154
	v_add_f32_e32 v155, 1.0, v155
	v_add_f32_e32 v156, 1.0, v156
	v_add_f32_e32 v157, 1.0, v157
	v_rcp_f32_e32 v154, v154
	v_rcp_f32_e32 v155, v155
	v_rcp_f32_e32 v156, v156
	v_rcp_f32_e32 v157, v157
	v_lshlrev_b32_e32 v150, 16, v182
	v_and_b32_e32 v151, 0xffff0000, v182
	v_lshlrev_b32_e32 v152, 16, v183
	v_and_b32_e32 v153, 0xffff0000, v183
	v_pk_fma_f32 v[86:87], v[154:155], v[150:151], v[146:147]
	v_pk_fma_f32 v[88:89], v[156:157], v[152:153], v[148:149]
	v_pk_fma_f32 v[194:195], v[86:87], v[86:87], v[194:195]
	v_pk_fma_f32 v[196:197], v[88:89], v[88:89], v[196:197]
	v_cvt_f32_i32_e32 v82, v82
	v_cvt_f32_i32_e32 v83, v83
	v_cvt_f32_i32_e32 v84, v84
	v_cvt_f32_i32_e32 v85, v85
	v_pk_mul_f32 v[142:143], v[234:235], v[188:189] op_sel_hi:[1,0]
	v_pk_mul_f32 v[144:145], v[236:237], v[188:189] op_sel_hi:[1,0]
	v_pk_fma_f32 v[154:155], v[142:143], v[82:83], v[218:219]
	v_pk_fma_f32 v[156:157], v[144:145], v[84:85], v[220:221]
	v_mul_f32_e32 v154, 0xbfb8aa3b, v154
	v_mul_f32_e32 v155, 0xbfb8aa3b, v155
	v_mul_f32_e32 v156, 0xbfb8aa3b, v156
	v_mul_f32_e32 v157, 0xbfb8aa3b, v157
	v_exp_f32_e32 v154, v154
	v_exp_f32_e32 v155, v155
	v_exp_f32_e32 v156, v156
	v_exp_f32_e32 v157, v157
	v_lshlrev_b32_e32 v146, 16, v176
	v_and_b32_e32 v147, 0xffff0000, v176
	v_lshlrev_b32_e32 v148, 16, v177
	v_and_b32_e32 v149, 0xffff0000, v177
	v_add_f32_e32 v154, 1.0, v154
	v_add_f32_e32 v155, 1.0, v155
	v_add_f32_e32 v156, 1.0, v156
	v_add_f32_e32 v157, 1.0, v157
	v_rcp_f32_e32 v154, v154
	v_rcp_f32_e32 v155, v155
	v_rcp_f32_e32 v156, v156
	v_rcp_f32_e32 v157, v157
	v_lshlrev_b32_e32 v150, 16, v184
	v_and_b32_e32 v151, 0xffff0000, v184
	v_lshlrev_b32_e32 v152, 16, v185
	v_and_b32_e32 v153, 0xffff0000, v185
	v_pk_fma_f32 v[82:83], v[154:155], v[150:151], v[146:147]
	v_pk_fma_f32 v[84:85], v[156:157], v[152:153], v[148:149]
	v_pk_fma_f32 v[194:195], v[82:83], v[82:83], v[194:195]
	v_pk_fma_f32 v[196:197], v[84:85], v[84:85], v[196:197]
	v_add_f32_e32 v194, v194, v195
	v_add_f32_e32 v196, v196, v197
	v_add_f32_e32 v194, v194, v196
	ds_bpermute_b32 v195, v58, v194
	s_waitcnt lgkmcnt(0)
; __device__ __forceinline__ f32x4 acc_i2f(const f32x4 a) { return __builtin_convertvector(__builtin_bit_cast(i32x4, a), f32x4); }
;     __device__ __forceinline__ void operator()(const f32x4 (&acc)[2][2][4][2], const pg8::Unit& u, int wr, int wc, int fr, int fq) const {
;     ...
;                 for (int mm = 0; mm < 2; ++mm) { const int m = 2 * mp + mm, row = row0 + ai * 128 + m * 16; f32x4 ssv = {0.f, 0.f, 0.f, 0.f}; const float sa = (QCLIP / 127.f) * sqrtf(q1v[mm] * (1.f / DM) + EPS);
; #pragma unroll
;                     for (int bj = 0; bj < 2; ++bj) { const size_t off = (size_t)row * DM + col0 + bj * 128;
;                         f32x4 p0, p1, x0, x1; unpack8v(pr[mm][bj], p0, p1); unpack8v(hr[mm][bj], x0, x1);
;                         const f32x4 g0 = acc_i2f(acc[ai][bj][m][0]) * (sb[bj][0] * sa) + bv[bj][0], g1 = acc_i2f(acc[ai][bj][m][1]) * (sb[bj][1] * sa) + bv[bj][1];
;                         const f32x4 h0 = x0 + p0 * sigm4(g0), h1 = x1 + p1 * sigm4(g1);
;                         *(f32x4*)(H + off) = h0; *(f32x4*)(H + off + 4) = h1;
;                         ssv = ssv + h0 * h0; ssv = ssv + h1 * h1; }
;                     float ss = (ssv[0] + ssv[1]) + (ssv[2] + ssv[3]);
;                     ss += __shfl_xor(ss, 16); ss += __shfl_xor(ss, 32);
;                     if (fq == 0) unsafeAtomicAdd(rss3 + row, ss); }
	v_add_f32_e32 v194, v194, v195
	ds_bpermute_b32 v195, v59, v194
	s_waitcnt lgkmcnt(0)
	v_add_f32_e32 v194, v194, v195
	s_and_saveexec_b64 s[32:33], s[6:7]
	global_atomic_add_f32 v54, v194, s[70:71] offset:192
	s_or_b64 exec, exec, s[32:33]
	global_load_dword v67, v54, s[68:69] offset:576
	global_load_dwordx4 v[170:173], v56, s[86:87] nt
	global_load_dwordx4 v[174:177], v56, s[86:87] offset:256 nt
	global_load_dwordx4 v[178:181], v56, s[88:89] nt
	global_load_dwordx4 v[182:185], v56, s[88:89] offset:256 nt
	s_add_u32 s86, s86, 0x20000
	s_addc_u32 s87, s87, 0
	s_add_u32 s88, s88, 0x20000
	s_addc_u32 s89, s89, 0
	s_waitcnt vmcnt(6)
	v_fmamk_f32 v186, v66, 0x39800000, v204
	v_mul_f32_e32 v187, 0x4f800000, v186
	v_cmp_gt_f32_e32 vcc, s67, v186
	s_nop 1
	v_cndmask_b32_e32 v186, v186, v187, vcc
	v_sqrt_f32_e32 v190, v186
	s_nop 0
	v_add_u32_e32 v191, -1, v190
	v_add_u32_e32 v192, 1, v190
	v_fma_f32 v193, -v191, v190, v186
	v_fma_f32 v187, -v192, v190, v186
	v_cmp_ge_f32_e64 s[10:11], 0, v193
	s_nop 1
	v_cndmask_b32_e64 v190, v190, v191, s[10:11]
	v_cmp_lt_f32_e64 s[10:11], 0, v187
	s_nop 1
	v_cndmask_b32_e64 v190, v190, v192, s[10:11]
	v_mul_f32_e32 v191, 0x37800000, v190
	v_cndmask_b32_e32 v190, v190, v191, vcc
	v_cmp_class_f32_e32 vcc, v186, v205
	s_nop 1
	v_cndmask_b32_e32 v186, v190, v186, vcc
	v_mul_f32_e32 v188, 0x3d112245, v186
	v_cvt_f32_i32_e32 v78, v78
	v_cvt_f32_i32_e32 v79, v79
	v_cvt_f32_i32_e32 v80, v80
	v_cvt_f32_i32_e32 v81, v81
	v_pk_mul_f32 v[142:143], v[222:223], v[188:189] op_sel_hi:[1,0]
	v_pk_mul_f32 v[144:145], v[224:225], v[188:189] op_sel_hi:[1,0]
	v_pk_fma_f32 v[154:155], v[142:143], v[78:79], v[206:207]
	v_pk_fma_f32 v[156:157], v[144:145], v[80:81], v[208:209]
	v_mul_f32_e32 v154, 0xbfb8aa3b, v154
	v_mul_f32_e32 v155, 0xbfb8aa3b, v155
	v_mul_f32_e32 v156, 0xbfb8aa3b, v156
	v_mul_f32_e32 v157, 0xbfb8aa3b, v157
	v_exp_f32_e32 v154, v154
	v_exp_f32_e32 v155, v155
	v_exp_f32_e32 v156, v156
	v_exp_f32_e32 v157, v157
	v_lshlrev_b32_e32 v146, 16, v238
	v_and_b32_e32 v147, 0xffff0000, v238
	v_lshlrev_b32_e32 v148, 16, v239
	v_and_b32_e32 v149, 0xffff0000, v239
	v_add_f32_e32 v154, 1.0, v154
	v_add_f32_e32 v155, 1.0, v155
	v_add_f32_e32 v156, 1.0, v156
	v_add_f32_e32 v157, 1.0, v157
	v_rcp_f32_e32 v154, v154
	v_rcp_f32_e32 v155, v155
	v_rcp_f32_e32 v156, v156
	v_rcp_f32_e32 v157, v157
	v_lshlrev_b32_e32 v150, 16, v246
	v_and_b32_e32 v151, 0xffff0000, v246
	v_lshlrev_b32_e32 v152, 16, v247
	v_and_b32_e32 v153, 0xffff0000, v247
	v_pk_fma_f32 v[78:79], v[154:155], v[150:151], v[146:147]
	v_pk_fma_f32 v[80:81], v[156:157], v[152:153], v[148:149]
	v_pk_mul_f32 v[194:195], v[78:79], v[78:79]
	v_pk_mul_f32 v[196:197], v[80:81], v[80:81]
	v_cvt_f32_i32_e32 v74, v74
	v_cvt_f32_i32_e32 v75, v75
	v_cvt_f32_i32_e32 v76, v76
	v_cvt_f32_i32_e32 v77, v77
	v_pk_mul_f32 v[142:143], v[226:227], v[188:189] op_sel_hi:[1,0]
	v_pk_mul_f32 v[144:145], v[228:229], v[188:189] op_sel_hi:[1,0]
	v_pk_fma_f32 v[154:155], v[142:143], v[74:75], v[210:211]
	v_pk_fma_f32 v[156:157], v[144:145], v[76:77], v[212:213]
	v_mul_f32_e32 v154, 0xbfb8aa3b, v154
	v_mul_f32_e32 v155, 0xbfb8aa3b, v155
	v_mul_f32_e32 v156, 0xbfb8aa3b, v156
	v_mul_f32_e32 v157, 0xbfb8aa3b, v157
	v_exp_f32_e32 v154, v154
	v_exp_f32_e32 v155, v155
	v_exp_f32_e32 v156, v156
	v_exp_f32_e32 v157, v157
	v_lshlrev_b32_e32 v146, 16, v240
	v_and_b32_e32 v147, 0xffff0000, v240
	v_lshlrev_b32_e32 v148, 16, v241
	v_and_b32_e32 v149, 0xffff0000, v241
	v_add_f32_e32 v154, 1.0, v154
	v_add_f32_e32 v155, 1.0, v155
	v_add_f32_e32 v156, 1.0, v156
	v_add_f32_e32 v157, 1.0, v157
	v_rcp_f32_e32 v154, v154
	v_rcp_f32_e32 v155, v155
	v_rcp_f32_e32 v156, v156
	v_rcp_f32_e32 v157, v157
	v_lshlrev_b32_e32 v150, 16, v248
	v_and_b32_e32 v151, 0xffff0000, v248
	v_lshlrev_b32_e32 v152, 16, v249
	v_and_b32_e32 v153, 0xffff0000, v249
	v_pk_fma_f32 v[74:75], v[154:155], v[150:151], v[146:147]
	v_pk_fma_f32 v[76:77], v[156:157], v[152:153], v[148:149]
	v_pk_fma_f32 v[194:195], v[74:75], v[74:75], v[194:195]
	v_pk_fma_f32 v[196:197], v[76:77], v[76:77], v[196:197]
	v_cvt_f32_i32_e32 v70, v70
	v_cvt_f32_i32_e32 v71, v71
	v_cvt_f32_i32_e32 v72, v72
	v_cvt_f32_i32_e32 v73, v73
	v_pk_mul_f32 v[142:143], v[230:231], v[188:189] op_sel_hi:[1,0]
	v_pk_mul_f32 v[144:145], v[232:233], v[188:189] op_sel_hi:[1,0]
	v_pk_fma_f32 v[154:155], v[142:143], v[70:71], v[214:215]
	v_pk_fma_f32 v[156:157], v[144:145], v[72:73], v[216:217]
	v_mul_f32_e32 v154, 0xbfb8aa3b, v154
	v_mul_f32_e32 v155, 0xbfb8aa3b, v155
	v_mul_f32_e32 v156, 0xbfb8aa3b, v156
	v_mul_f32_e32 v157, 0xbfb8aa3b, v157
	v_exp_f32_e32 v154, v154
	v_exp_f32_e32 v155, v155
	v_exp_f32_e32 v156, v156
	v_exp_f32_e32 v157, v157
	v_lshlrev_b32_e32 v146, 16, v242
	v_and_b32_e32 v147, 0xffff0000, v242
	v_lshlrev_b32_e32 v148, 16, v243
	v_and_b32_e32 v149, 0xffff0000, v243
	v_add_f32_e32 v154, 1.0, v154
	v_add_f32_e32 v155, 1.0, v155
	v_add_f32_e32 v156, 1.0, v156
	v_add_f32_e32 v157, 1.0, v157
	v_rcp_f32_e32 v154, v154
	v_rcp_f32_e32 v155, v155
	v_rcp_f32_e32 v156, v156
	v_rcp_f32_e32 v157, v157
	v_lshlrev_b32_e32 v150, 16, v250
	v_and_b32_e32 v151, 0xffff0000, v250
	v_lshlrev_b32_e32 v152, 16, v251
	v_and_b32_e32 v153, 0xffff0000, v251
	v_pk_fma_f32 v[70:71], v[154:155], v[150:151], v[146:147]
	v_pk_fma_f32 v[72:73], v[156:157], v[152:153], v[148:149]
	v_pk_fma_f32 v[194:195], v[70:71], v[70:71], v[194:195]
	v_pk_fma_f32 v[196:197], v[72:73], v[72:73], v[196:197]
	v_cvt_f32_i32_e32 v62, v62
	v_cvt_f32_i32_e32 v63, v63
	v_cvt_f32_i32_e32 v64, v64
	v_cvt_f32_i32_e32 v65, v65
	v_pk_mul_f32 v[142:143], v[234:235], v[188:189] op_sel_hi:[1,0]
	v_pk_mul_f32 v[144:145], v[236:237], v[188:189] op_sel_hi:[1,0]
	v_pk_fma_f32 v[154:155], v[142:143], v[62:63], v[218:219]
	v_pk_fma_f32 v[156:157], v[144:145], v[64:65], v[220:221]
	v_mul_f32_e32 v154, 0xbfb8aa3b, v154
	v_mul_f32_e32 v155, 0xbfb8aa3b, v155
	v_mul_f32_e32 v156, 0xbfb8aa3b, v156
	v_mul_f32_e32 v157, 0xbfb8aa3b, v157
	v_exp_f32_e32 v154, v154
	v_exp_f32_e32 v155, v155
	v_exp_f32_e32 v156, v156
	v_exp_f32_e32 v157, v157
	v_lshlrev_b32_e32 v146, 16, v244
	v_and_b32_e32 v147, 0xffff0000, v244
	v_lshlrev_b32_e32 v148, 16, v245
	v_and_b32_e32 v149, 0xffff0000, v245
	v_add_f32_e32 v154, 1.0, v154
	v_add_f32_e32 v155, 1.0, v155
	v_add_f32_e32 v156, 1.0, v156
	v_add_f32_e32 v157, 1.0, v157
	v_rcp_f32_e32 v154, v154
	v_rcp_f32_e32 v155, v155
	v_rcp_f32_e32 v156, v156
	v_rcp_f32_e32 v157, v157
	v_lshlrev_b32_e32 v150, 16, v252
	v_and_b32_e32 v151, 0xffff0000, v252
	v_lshlrev_b32_e32 v152, 16, v253
	v_and_b32_e32 v153, 0xffff0000, v253
	v_pk_fma_f32 v[62:63], v[154:155], v[150:151], v[146:147]
	v_pk_fma_f32 v[64:65], v[156:157], v[152:153], v[148:149]
	v_pk_fma_f32 v[194:195], v[62:63], v[62:63], v[194:195]
	v_pk_fma_f32 v[196:197], v[64:65], v[64:65], v[196:197]
	v_add_f32_e32 v194, v194, v195
	v_add_f32_e32 v196, v196, v197
	v_add_f32_e32 v194, v194, v196
	ds_bpermute_b32 v195, v58, v194
	s_waitcnt lgkmcnt(0)
; __device__ __forceinline__ f32x4 acc_i2f(const f32x4 a) { return __builtin_convertvector(__builtin_bit_cast(i32x4, a), f32x4); }
;     __device__ __forceinline__ void operator()(const f32x4 (&acc)[2][2][4][2], const pg8::Unit& u, int wr, int wc, int fr, int fq) const {
;     ...
;                 for (int mm = 0; mm < 2; ++mm) { const int m = 2 * mp + mm, row = row0 + ai * 128 + m * 16; f32x4 ssv = {0.f, 0.f, 0.f, 0.f}; const float sa = (QCLIP / 127.f) * sqrtf(q1v[mm] * (1.f / DM) + EPS);
; #pragma unroll
;                     for (int bj = 0; bj < 2; ++bj) { const size_t off = (size_t)row * DM + col0 + bj * 128;
;                         f32x4 p0, p1, x0, x1; unpack8v(pr[mm][bj], p0, p1); unpack8v(hr[mm][bj], x0, x1);
;                         const f32x4 g0 = acc_i2f(acc[ai][bj][m][0]) * (sb[bj][0] * sa) + bv[bj][0], g1 = acc_i2f(acc[ai][bj][m][1]) * (sb[bj][1] * sa) + bv[bj][1];
;                         const f32x4 h0 = x0 + p0 * sigm4(g0), h1 = x1 + p1 * sigm4(g1);
;                         *(f32x4*)(H + off) = h0; *(f32x4*)(H + off + 4) = h1;
;                         ssv = ssv + h0 * h0; ssv = ssv + h1 * h1; }
;                     float ss = (ssv[0] + ssv[1]) + (ssv[2] + ssv[3]);
;                     ss += __shfl_xor(ss, 16); ss += __shfl_xor(ss, 32);
;                     if (fq == 0) unsafeAtomicAdd(rss3 + row, ss); }
	v_add_f32_e32 v194, v194, v195
	ds_bpermute_b32 v195, v59, v194
	s_waitcnt lgkmcnt(0)
	v_add_f32_e32 v194, v194, v195
	s_and_saveexec_b64 s[32:33], s[6:7]
	global_atomic_add_f32 v54, v194, s[70:71] offset:512
	s_or_b64 exec, exec, s[32:33]
	global_load_dword v66, v54, s[68:69] offset:640
	global_load_dwordx4 v[238:241], v56, s[86:87] nt
	global_load_dwordx4 v[242:245], v56, s[86:87] offset:256 nt
	global_load_dwordx4 v[246:249], v56, s[88:89] nt
	global_load_dwordx4 v[250:253], v56, s[88:89] offset:256 nt
	s_add_u32 s86, s86, 0x20000
	s_addc_u32 s87, s87, 0
	s_add_u32 s88, s88, 0x20000
	s_addc_u32 s89, s89, 0
	s_waitcnt vmcnt(6)
	v_fmamk_f32 v186, v67, 0x39800000, v204
	v_mul_f32_e32 v187, 0x4f800000, v186
	v_cmp_gt_f32_e32 vcc, s67, v186
	s_nop 1
	v_cndmask_b32_e32 v186, v186, v187, vcc
	v_sqrt_f32_e32 v190, v186
	s_nop 0
	v_add_u32_e32 v191, -1, v190
	v_add_u32_e32 v192, 1, v190
	v_fma_f32 v193, -v191, v190, v186
	v_fma_f32 v187, -v192, v190, v186
	v_cmp_ge_f32_e64 s[10:11], 0, v193
	s_nop 1
	v_cndmask_b32_e64 v190, v190, v191, s[10:11]
	v_cmp_lt_f32_e64 s[10:11], 0, v187
	s_nop 1
	v_cndmask_b32_e64 v190, v190, v192, s[10:11]
	v_mul_f32_e32 v191, 0x37800000, v190
	v_cndmask_b32_e32 v190, v190, v191, vcc
	v_cmp_class_f32_e32 vcc, v186, v205
	s_nop 1
	v_cndmask_b32_e32 v186, v190, v186, vcc
	v_mul_f32_e32 v188, 0x3d112245, v186
	v_cvt_f32_i32_e32 v46, v46
	v_cvt_f32_i32_e32 v47, v47
	v_cvt_f32_i32_e32 v48, v48
	v_cvt_f32_i32_e32 v49, v49
	v_pk_mul_f32 v[142:143], v[222:223], v[188:189] op_sel_hi:[1,0]
	v_pk_mul_f32 v[144:145], v[224:225], v[188:189] op_sel_hi:[1,0]
	v_pk_fma_f32 v[154:155], v[142:143], v[46:47], v[206:207]
	v_pk_fma_f32 v[156:157], v[144:145], v[48:49], v[208:209]
	v_mul_f32_e32 v154, 0xbfb8aa3b, v154
	v_mul_f32_e32 v155, 0xbfb8aa3b, v155
	v_mul_f32_e32 v156, 0xbfb8aa3b, v156
	v_mul_f32_e32 v157, 0xbfb8aa3b, v157
	v_exp_f32_e32 v154, v154
	v_exp_f32_e32 v155, v155
	v_exp_f32_e32 v156, v156
	v_exp_f32_e32 v157, v157
	v_lshlrev_b32_e32 v146, 16, v170
	v_and_b32_e32 v147, 0xffff0000, v170
	v_lshlrev_b32_e32 v148, 16, v171
	v_and_b32_e32 v149, 0xffff0000, v171
	v_add_f32_e32 v154, 1.0, v154
	v_add_f32_e32 v155, 1.0, v155
	v_add_f32_e32 v156, 1.0, v156
	v_add_f32_e32 v157, 1.0, v157
	v_rcp_f32_e32 v154, v154
	v_rcp_f32_e32 v155, v155
	v_rcp_f32_e32 v156, v156
	v_rcp_f32_e32 v157, v157
	v_lshlrev_b32_e32 v150, 16, v178
	v_and_b32_e32 v151, 0xffff0000, v178
	v_lshlrev_b32_e32 v152, 16, v179
	v_and_b32_e32 v153, 0xffff0000, v179
	v_pk_fma_f32 v[46:47], v[154:155], v[150:151], v[146:147]
	v_pk_fma_f32 v[48:49], v[156:157], v[152:153], v[148:149]
	v_pk_mul_f32 v[194:195], v[46:47], v[46:47]
	v_pk_mul_f32 v[196:197], v[48:49], v[48:49]
	v_cvt_f32_i32_e32 v42, v42
	v_cvt_f32_i32_e32 v43, v43
	v_cvt_f32_i32_e32 v44, v44
	v_cvt_f32_i32_e32 v45, v45
	v_pk_mul_f32 v[142:143], v[226:227], v[188:189] op_sel_hi:[1,0]
	v_pk_mul_f32 v[144:145], v[228:229], v[188:189] op_sel_hi:[1,0]
	v_pk_fma_f32 v[154:155], v[142:143], v[42:43], v[210:211]
	v_pk_fma_f32 v[156:157], v[144:145], v[44:45], v[212:213]
	v_mul_f32_e32 v154, 0xbfb8aa3b, v154
	v_mul_f32_e32 v155, 0xbfb8aa3b, v155
	v_mul_f32_e32 v156, 0xbfb8aa3b, v156
	v_mul_f32_e32 v157, 0xbfb8aa3b, v157
	v_exp_f32_e32 v154, v154
	v_exp_f32_e32 v155, v155
	v_exp_f32_e32 v156, v156
	v_exp_f32_e32 v157, v157
	v_lshlrev_b32_e32 v146, 16, v172
	v_and_b32_e32 v147, 0xffff0000, v172
	v_lshlrev_b32_e32 v148, 16, v173
	v_and_b32_e32 v149, 0xffff0000, v173
	v_add_f32_e32 v154, 1.0, v154
	v_add_f32_e32 v155, 1.0, v155
	v_add_f32_e32 v156, 1.0, v156
	v_add_f32_e32 v157, 1.0, v157
	v_rcp_f32_e32 v154, v154
	v_rcp_f32_e32 v155, v155
	v_rcp_f32_e32 v156, v156
	v_rcp_f32_e32 v157, v157
	v_lshlrev_b32_e32 v150, 16, v180
	v_and_b32_e32 v151, 0xffff0000, v180
	v_lshlrev_b32_e32 v152, 16, v181
	v_and_b32_e32 v153, 0xffff0000, v181
	v_pk_fma_f32 v[42:43], v[154:155], v[150:151], v[146:147]
	v_pk_fma_f32 v[44:45], v[156:157], v[152:153], v[148:149]
	v_pk_fma_f32 v[194:195], v[42:43], v[42:43], v[194:195]
	v_pk_fma_f32 v[196:197], v[44:45], v[44:45], v[196:197]
	v_cvt_f32_i32_e32 v38, v38
	v_cvt_f32_i32_e32 v39, v39
	v_cvt_f32_i32_e32 v40, v40
	v_cvt_f32_i32_e32 v41, v41
	v_pk_mul_f32 v[142:143], v[230:231], v[188:189] op_sel_hi:[1,0]
	v_pk_mul_f32 v[144:145], v[232:233], v[188:189] op_sel_hi:[1,0]
	v_pk_fma_f32 v[154:155], v[142:143], v[38:39], v[214:215]
	v_pk_fma_f32 v[156:157], v[144:145], v[40:41], v[216:217]
	v_mul_f32_e32 v154, 0xbfb8aa3b, v154
	v_mul_f32_e32 v155, 0xbfb8aa3b, v155
	v_mul_f32_e32 v156, 0xbfb8aa3b, v156
	v_mul_f32_e32 v157, 0xbfb8aa3b, v157
	v_exp_f32_e32 v154, v154
	v_exp_f32_e32 v155, v155
	v_exp_f32_e32 v156, v156
	v_exp_f32_e32 v157, v157
	v_lshlrev_b32_e32 v146, 16, v174
	v_and_b32_e32 v147, 0xffff0000, v174
	v_lshlrev_b32_e32 v148, 16, v175
	v_and_b32_e32 v149, 0xffff0000, v175
	v_add_f32_e32 v154, 1.0, v154
	v_add_f32_e32 v155, 1.0, v155
	v_add_f32_e32 v156, 1.0, v156
	v_add_f32_e32 v157, 1.0, v157
	v_rcp_f32_e32 v154, v154
	v_rcp_f32_e32 v155, v155
	v_rcp_f32_e32 v156, v156
	v_rcp_f32_e32 v157, v157
	v_lshlrev_b32_e32 v150, 16, v182
	v_and_b32_e32 v151, 0xffff0000, v182
	v_lshlrev_b32_e32 v152, 16, v183
	v_and_b32_e32 v153, 0xffff0000, v183
	v_pk_fma_f32 v[38:39], v[154:155], v[150:151], v[146:147]
	v_pk_fma_f32 v[40:41], v[156:157], v[152:153], v[148:149]
	v_pk_fma_f32 v[194:195], v[38:39], v[38:39], v[194:195]
	v_pk_fma_f32 v[196:197], v[40:41], v[40:41], v[196:197]
	v_cvt_f32_i32_e32 v34, v34
	v_cvt_f32_i32_e32 v35, v35
	v_cvt_f32_i32_e32 v36, v36
	v_cvt_f32_i32_e32 v37, v37
	v_pk_mul_f32 v[142:143], v[234:235], v[188:189] op_sel_hi:[1,0]
	v_pk_mul_f32 v[144:145], v[236:237], v[188:189] op_sel_hi:[1,0]
	v_pk_fma_f32 v[154:155], v[142:143], v[34:35], v[218:219]
	v_pk_fma_f32 v[156:157], v[144:145], v[36:37], v[220:221]
	v_mul_f32_e32 v154, 0xbfb8aa3b, v154
	v_mul_f32_e32 v155, 0xbfb8aa3b, v155
	v_mul_f32_e32 v156, 0xbfb8aa3b, v156
	v_mul_f32_e32 v157, 0xbfb8aa3b, v157
	v_exp_f32_e32 v154, v154
	v_exp_f32_e32 v155, v155
	v_exp_f32_e32 v156, v156
	v_exp_f32_e32 v157, v157
	v_lshlrev_b32_e32 v146, 16, v176
	v_and_b32_e32 v147, 0xffff0000, v176
	v_lshlrev_b32_e32 v148, 16, v177
	v_and_b32_e32 v149, 0xffff0000, v177
	v_add_f32_e32 v154, 1.0, v154
	v_add_f32_e32 v155, 1.0, v155
	v_add_f32_e32 v156, 1.0, v156
	v_add_f32_e32 v157, 1.0, v157
	v_rcp_f32_e32 v154, v154
	v_rcp_f32_e32 v155, v155
	v_rcp_f32_e32 v156, v156
	v_rcp_f32_e32 v157, v157
	v_lshlrev_b32_e32 v150, 16, v184
	v_and_b32_e32 v151, 0xffff0000, v184
	v_lshlrev_b32_e32 v152, 16, v185
	v_and_b32_e32 v153, 0xffff0000, v185
	v_pk_fma_f32 v[34:35], v[154:155], v[150:151], v[146:147]
	v_pk_fma_f32 v[36:37], v[156:157], v[152:153], v[148:149]
	v_pk_fma_f32 v[194:195], v[34:35], v[34:35], v[194:195]
	v_pk_fma_f32 v[196:197], v[36:37], v[36:37], v[196:197]
	v_add_f32_e32 v194, v194, v195
	v_add_f32_e32 v196, v196, v197
	v_add_f32_e32 v194, v194, v196
	ds_bpermute_b32 v195, v58, v194
	s_waitcnt lgkmcnt(0)
; __device__ __forceinline__ f32x4 acc_i2f(const f32x4 a) { return __builtin_convertvector(__builtin_bit_cast(i32x4, a), f32x4); }
;     __device__ __forceinline__ void operator()(const f32x4 (&acc)[2][2][4][2], const pg8::Unit& u, int wr, int wc, int fr, int fq) const {
;     ...
;                 u32x4 hr[2][2], pr[2][2]; float q1v[2];
; #pragma unroll
;                 for (int mm = 0; mm < 2; ++mm) { const int row = row0 + ai * 128 + (2 * mp + mm) * 16; q1v[mm] = rss1[row];
; #pragma unroll
;                     for (int bj = 0; bj < 2; ++bj) { const size_t off = (size_t)row * DM + col0 + bj * 128; hr[mm][bj] = *(const u32x4*)(HB + off); pr[mm][bj] = *(const u32x4*)(PP + off); } }
; #pragma unroll
;                 for (int mm = 0; mm < 2; ++mm) { const int m = 2 * mp + mm, row = row0 + ai * 128 + m * 16; f32x4 ssv = {0.f, 0.f, 0.f, 0.f}; const float sa = (QCLIP / 127.f) * sqrtf(q1v[mm] * (1.f / DM) + EPS);
; #pragma unroll
;                     for (int bj = 0; bj < 2; ++bj) { const size_t off = (size_t)row * DM + col0 + bj * 128;
;                         f32x4 p0, p1, x0, x1; unpack8v(pr[mm][bj], p0, p1); unpack8v(hr[mm][bj], x0, x1);
;                         const f32x4 g0 = acc_i2f(acc[ai][bj][m][0]) * (sb[bj][0] * sa) + bv[bj][0], g1 = acc_i2f(acc[ai][bj][m][1]) * (sb[bj][1] * sa) + bv[bj][1];
;                         const f32x4 h0 = x0 + p0 * sigm4(g0), h1 = x1 + p1 * sigm4(g1);
;                         *(f32x4*)(H + off) = h0; *(f32x4*)(H + off + 4) = h1;
;                         ssv = ssv + h0 * h0; ssv = ssv + h1 * h1; }
;                     float ss = (ssv[0] + ssv[1]) + (ssv[2] + ssv[3]);
;                     ss += __shfl_xor(ss, 16); ss += __shfl_xor(ss, 32);
;                     if (fq == 0) unsafeAtomicAdd(rss3 + row, ss); }
	v_add_f32_e32 v194, v194, v195
	ds_bpermute_b32 v195, v59, v194
	s_waitcnt lgkmcnt(0)
	v_add_f32_e32 v194, v194, v195
	s_and_saveexec_b64 s[32:33], s[6:7]
	global_atomic_add_f32 v54, v194, s[70:71] offset:576
	s_or_b64 exec, exec, s[32:33]
	global_load_dword v67, v54, s[68:69] offset:704
	global_load_dwordx4 v[170:173], v56, s[86:87] nt
	global_load_dwordx4 v[174:177], v56, s[86:87] offset:256 nt
	global_load_dwordx4 v[178:181], v56, s[88:89] nt
	global_load_dwordx4 v[182:185], v56, s[88:89] offset:256 nt
	s_waitcnt vmcnt(6)
	v_fmamk_f32 v186, v66, 0x39800000, v204
	v_mul_f32_e32 v187, 0x4f800000, v186
	v_cmp_gt_f32_e32 vcc, s67, v186
	s_nop 1
	v_cndmask_b32_e32 v186, v186, v187, vcc
	v_sqrt_f32_e32 v190, v186
	s_nop 0
	v_add_u32_e32 v191, -1, v190
	v_add_u32_e32 v192, 1, v190
	v_fma_f32 v193, -v191, v190, v186
	v_fma_f32 v187, -v192, v190, v186
	v_cmp_ge_f32_e64 s[10:11], 0, v193
	s_nop 1
	v_cndmask_b32_e64 v190, v190, v191, s[10:11]
	v_cmp_lt_f32_e64 s[10:11], 0, v187
	s_nop 1
	v_cndmask_b32_e64 v190, v190, v192, s[10:11]
	v_mul_f32_e32 v191, 0x37800000, v190
	v_cndmask_b32_e32 v190, v190, v191, vcc
	v_cmp_class_f32_e32 vcc, v186, v205
	s_nop 1
	v_cndmask_b32_e32 v186, v190, v186, vcc
	v_mul_f32_e32 v188, 0x3d112245, v186
	v_cvt_f32_i32_e32 v30, v30
	v_cvt_f32_i32_e32 v31, v31
	v_cvt_f32_i32_e32 v32, v32
	v_cvt_f32_i32_e32 v33, v33
	v_pk_mul_f32 v[142:143], v[222:223], v[188:189] op_sel_hi:[1,0]
	v_pk_mul_f32 v[144:145], v[224:225], v[188:189] op_sel_hi:[1,0]
	v_pk_fma_f32 v[154:155], v[142:143], v[30:31], v[206:207]
	v_pk_fma_f32 v[156:157], v[144:145], v[32:33], v[208:209]
	v_mul_f32_e32 v154, 0xbfb8aa3b, v154
	v_mul_f32_e32 v155, 0xbfb8aa3b, v155
	v_mul_f32_e32 v156, 0xbfb8aa3b, v156
	v_mul_f32_e32 v157, 0xbfb8aa3b, v157
	v_exp_f32_e32 v154, v154
	v_exp_f32_e32 v155, v155
	v_exp_f32_e32 v156, v156
	v_exp_f32_e32 v157, v157
	v_lshlrev_b32_e32 v146, 16, v238
	v_and_b32_e32 v147, 0xffff0000, v238
	v_lshlrev_b32_e32 v148, 16, v239
	v_and_b32_e32 v149, 0xffff0000, v239
	v_add_f32_e32 v154, 1.0, v154
	v_add_f32_e32 v155, 1.0, v155
	v_add_f32_e32 v156, 1.0, v156
	v_add_f32_e32 v157, 1.0, v157
	v_rcp_f32_e32 v154, v154
	v_rcp_f32_e32 v155, v155
	v_rcp_f32_e32 v156, v156
	v_rcp_f32_e32 v157, v157
	v_lshlrev_b32_e32 v150, 16, v246
	v_and_b32_e32 v151, 0xffff0000, v246
	v_lshlrev_b32_e32 v152, 16, v247
	v_and_b32_e32 v153, 0xffff0000, v247
	v_pk_fma_f32 v[30:31], v[154:155], v[150:151], v[146:147]
	v_pk_fma_f32 v[32:33], v[156:157], v[152:153], v[148:149]
	v_pk_mul_f32 v[194:195], v[30:31], v[30:31]
	v_pk_mul_f32 v[196:197], v[32:33], v[32:33]
	v_cvt_f32_i32_e32 v26, v26
	v_cvt_f32_i32_e32 v27, v27
	v_cvt_f32_i32_e32 v28, v28
	v_cvt_f32_i32_e32 v29, v29
	v_pk_mul_f32 v[142:143], v[226:227], v[188:189] op_sel_hi:[1,0]
	v_pk_mul_f32 v[144:145], v[228:229], v[188:189] op_sel_hi:[1,0]
	v_pk_fma_f32 v[154:155], v[142:143], v[26:27], v[210:211]
	v_pk_fma_f32 v[156:157], v[144:145], v[28:29], v[212:213]
	v_mul_f32_e32 v154, 0xbfb8aa3b, v154
	v_mul_f32_e32 v155, 0xbfb8aa3b, v155
	v_mul_f32_e32 v156, 0xbfb8aa3b, v156
	v_mul_f32_e32 v157, 0xbfb8aa3b, v157
	v_exp_f32_e32 v154, v154
	v_exp_f32_e32 v155, v155
	v_exp_f32_e32 v156, v156
	v_exp_f32_e32 v157, v157
	v_lshlrev_b32_e32 v146, 16, v240
	v_and_b32_e32 v147, 0xffff0000, v240
	v_lshlrev_b32_e32 v148, 16, v241
	v_and_b32_e32 v149, 0xffff0000, v241
	v_add_f32_e32 v154, 1.0, v154
	v_add_f32_e32 v155, 1.0, v155
	v_add_f32_e32 v156, 1.0, v156
	v_add_f32_e32 v157, 1.0, v157
	v_rcp_f32_e32 v154, v154
	v_rcp_f32_e32 v155, v155
	v_rcp_f32_e32 v156, v156
	v_rcp_f32_e32 v157, v157
	v_lshlrev_b32_e32 v150, 16, v248
	v_and_b32_e32 v151, 0xffff0000, v248
	v_lshlrev_b32_e32 v152, 16, v249
	v_and_b32_e32 v153, 0xffff0000, v249
	v_pk_fma_f32 v[26:27], v[154:155], v[150:151], v[146:147]
	v_pk_fma_f32 v[28:29], v[156:157], v[152:153], v[148:149]
	v_pk_fma_f32 v[194:195], v[26:27], v[26:27], v[194:195]
	v_pk_fma_f32 v[196:197], v[28:29], v[28:29], v[196:197]
	v_cvt_f32_i32_e32 v22, v22
	v_cvt_f32_i32_e32 v23, v23
	v_cvt_f32_i32_e32 v24, v24
	v_cvt_f32_i32_e32 v25, v25
	v_pk_mul_f32 v[142:143], v[230:231], v[188:189] op_sel_hi:[1,0]
	v_pk_mul_f32 v[144:145], v[232:233], v[188:189] op_sel_hi:[1,0]
	v_pk_fma_f32 v[154:155], v[142:143], v[22:23], v[214:215]
	v_pk_fma_f32 v[156:157], v[144:145], v[24:25], v[216:217]
	v_mul_f32_e32 v154, 0xbfb8aa3b, v154
	v_mul_f32_e32 v155, 0xbfb8aa3b, v155
	v_mul_f32_e32 v156, 0xbfb8aa3b, v156
	v_mul_f32_e32 v157, 0xbfb8aa3b, v157
	v_exp_f32_e32 v154, v154
	v_exp_f32_e32 v155, v155
	v_exp_f32_e32 v156, v156
	v_exp_f32_e32 v157, v157
	v_lshlrev_b32_e32 v146, 16, v242
	v_and_b32_e32 v147, 0xffff0000, v242
	v_lshlrev_b32_e32 v148, 16, v243
	v_and_b32_e32 v149, 0xffff0000, v243
	v_add_f32_e32 v154, 1.0, v154
	v_add_f32_e32 v155, 1.0, v155
	v_add_f32_e32 v156, 1.0, v156
	v_add_f32_e32 v157, 1.0, v157
	v_rcp_f32_e32 v154, v154
	v_rcp_f32_e32 v155, v155
	v_rcp_f32_e32 v156, v156
	v_rcp_f32_e32 v157, v157
	v_lshlrev_b32_e32 v150, 16, v250
	v_and_b32_e32 v151, 0xffff0000, v250
	v_lshlrev_b32_e32 v152, 16, v251
	v_and_b32_e32 v153, 0xffff0000, v251
	v_pk_fma_f32 v[22:23], v[154:155], v[150:151], v[146:147]
	v_pk_fma_f32 v[24:25], v[156:157], v[152:153], v[148:149]
	v_pk_fma_f32 v[194:195], v[22:23], v[22:23], v[194:195]
	v_pk_fma_f32 v[196:197], v[24:25], v[24:25], v[196:197]
	v_cvt_f32_i32_e32 v18, v18
	v_cvt_f32_i32_e32 v19, v19
	v_cvt_f32_i32_e32 v20, v20
	v_cvt_f32_i32_e32 v21, v21
	v_pk_mul_f32 v[142:143], v[234:235], v[188:189] op_sel_hi:[1,0]
	v_pk_mul_f32 v[144:145], v[236:237], v[188:189] op_sel_hi:[1,0]
	v_pk_fma_f32 v[154:155], v[142:143], v[18:19], v[218:219]
	v_pk_fma_f32 v[156:157], v[144:145], v[20:21], v[220:221]
	v_mul_f32_e32 v154, 0xbfb8aa3b, v154
	v_mul_f32_e32 v155, 0xbfb8aa3b, v155
	v_mul_f32_e32 v156, 0xbfb8aa3b, v156
	v_mul_f32_e32 v157, 0xbfb8aa3b, v157
	v_exp_f32_e32 v154, v154
	v_exp_f32_e32 v155, v155
	v_exp_f32_e32 v156, v156
	v_exp_f32_e32 v157, v157
	v_lshlrev_b32_e32 v146, 16, v244
	v_and_b32_e32 v147, 0xffff0000, v244
	v_lshlrev_b32_e32 v148, 16, v245
	v_and_b32_e32 v149, 0xffff0000, v245
	v_add_f32_e32 v154, 1.0, v154
	v_add_f32_e32 v155, 1.0, v155
	v_add_f32_e32 v156, 1.0, v156
	v_add_f32_e32 v157, 1.0, v157
	v_rcp_f32_e32 v154, v154
	v_rcp_f32_e32 v155, v155
	v_rcp_f32_e32 v156, v156
	v_rcp_f32_e32 v157, v157
	v_lshlrev_b32_e32 v150, 16, v252
	v_and_b32_e32 v151, 0xffff0000, v252
	v_lshlrev_b32_e32 v152, 16, v253
	v_and_b32_e32 v153, 0xffff0000, v253
	v_pk_fma_f32 v[18:19], v[154:155], v[150:151], v[146:147]
	v_pk_fma_f32 v[20:21], v[156:157], v[152:153], v[148:149]
	v_pk_fma_f32 v[194:195], v[18:19], v[18:19], v[194:195]
	v_pk_fma_f32 v[196:197], v[20:21], v[20:21], v[196:197]
	v_add_f32_e32 v194, v194, v195
	v_add_f32_e32 v196, v196, v197
	v_add_f32_e32 v194, v194, v196
	ds_bpermute_b32 v195, v58, v194
	s_waitcnt lgkmcnt(0)
; __device__ __forceinline__ f32x4 acc_i2f(const f32x4 a) { return __builtin_convertvector(__builtin_bit_cast(i32x4, a), f32x4); }
;     __device__ __forceinline__ void operator()(const f32x4 (&acc)[2][2][4][2], const pg8::Unit& u, int wr, int wc, int fr, int fq) const {
;     ...
;                 u32x4 hr[2][2], pr[2][2]; float q1v[2];
; #pragma unroll
;                 for (int mm = 0; mm < 2; ++mm) { const int row = row0 + ai * 128 + (2 * mp + mm) * 16; q1v[mm] = rss1[row];
; #pragma unroll
;                     for (int bj = 0; bj < 2; ++bj) { const size_t off = (size_t)row * DM + col0 + bj * 128; hr[mm][bj] = *(const u32x4*)(HB + off); pr[mm][bj] = *(const u32x4*)(PP + off); } }
; #pragma unroll
;                 for (int mm = 0; mm < 2; ++mm) { const int m = 2 * mp + mm, row = row0 + ai * 128 + m * 16; f32x4 ssv = {0.f, 0.f, 0.f, 0.f}; const float sa = (QCLIP / 127.f) * sqrtf(q1v[mm] * (1.f / DM) + EPS);
; #pragma unroll
;                     for (int bj = 0; bj < 2; ++bj) { const size_t off = (size_t)row * DM + col0 + bj * 128;
;                         f32x4 p0, p1, x0, x1; unpack8v(pr[mm][bj], p0, p1); unpack8v(hr[mm][bj], x0, x1);
;                         const f32x4 g0 = acc_i2f(acc[ai][bj][m][0]) * (sb[bj][0] * sa) + bv[bj][0], g1 = acc_i2f(acc[ai][bj][m][1]) * (sb[bj][1] * sa) + bv[bj][1];
;                         const f32x4 h0 = x0 + p0 * sigm4(g0), h1 = x1 + p1 * sigm4(g1);
;                         *(f32x4*)(H + off) = h0; *(f32x4*)(H + off + 4) = h1;
;                         ssv = ssv + h0 * h0; ssv = ssv + h1 * h1; }
;                     float ss = (ssv[0] + ssv[1]) + (ssv[2] + ssv[3]);
;                     ss += __shfl_xor(ss, 16); ss += __shfl_xor(ss, 32);
;                     if (fq == 0) unsafeAtomicAdd(rss3 + row, ss); }
;                 asm volatile("" ::: "memory"); }
	v_add_f32_e32 v194, v194, v195
	ds_bpermute_b32 v195, v59, v194
	s_waitcnt lgkmcnt(0)
	v_add_f32_e32 v194, v194, v195
	s_and_saveexec_b64 s[32:33], s[6:7]
	global_atomic_add_f32 v54, v194, s[70:71] offset:640
	s_or_b64 exec, exec, s[32:33]
	s_waitcnt vmcnt(1)
	v_fmamk_f32 v186, v67, 0x39800000, v204
	v_mul_f32_e32 v187, 0x4f800000, v186
	v_cmp_gt_f32_e32 vcc, s67, v186
	s_nop 1
	v_cndmask_b32_e32 v186, v186, v187, vcc
	v_sqrt_f32_e32 v190, v186
	s_nop 0
	v_add_u32_e32 v191, -1, v190
	v_add_u32_e32 v192, 1, v190
	v_fma_f32 v193, -v191, v190, v186
	v_fma_f32 v187, -v192, v190, v186
	v_cmp_ge_f32_e64 s[10:11], 0, v193
	s_nop 1
	v_cndmask_b32_e64 v190, v190, v191, s[10:11]
	v_cmp_lt_f32_e64 s[10:11], 0, v187
	s_nop 1
	v_cndmask_b32_e64 v190, v190, v192, s[10:11]
	v_mul_f32_e32 v191, 0x37800000, v190
	v_cndmask_b32_e32 v190, v190, v191, vcc
	v_cmp_class_f32_e32 vcc, v186, v205
	s_nop 1
	v_cndmask_b32_e32 v186, v190, v186, vcc
	v_mul_f32_e32 v188, 0x3d112245, v186
	v_cvt_f32_i32_e32 v14, v14
	v_cvt_f32_i32_e32 v15, v15
	v_cvt_f32_i32_e32 v16, v16
	v_cvt_f32_i32_e32 v17, v17
	v_pk_mul_f32 v[142:143], v[222:223], v[188:189] op_sel_hi:[1,0]
	v_pk_mul_f32 v[144:145], v[224:225], v[188:189] op_sel_hi:[1,0]
	v_pk_fma_f32 v[154:155], v[142:143], v[14:15], v[206:207]
	v_pk_fma_f32 v[156:157], v[144:145], v[16:17], v[208:209]
	v_mul_f32_e32 v154, 0xbfb8aa3b, v154
	v_mul_f32_e32 v155, 0xbfb8aa3b, v155
	v_mul_f32_e32 v156, 0xbfb8aa3b, v156
	v_mul_f32_e32 v157, 0xbfb8aa3b, v157
	v_exp_f32_e32 v154, v154
	v_exp_f32_e32 v155, v155
	v_exp_f32_e32 v156, v156
	v_exp_f32_e32 v157, v157
	v_lshlrev_b32_e32 v146, 16, v170
	v_and_b32_e32 v147, 0xffff0000, v170
	v_lshlrev_b32_e32 v148, 16, v171
	v_and_b32_e32 v149, 0xffff0000, v171
	v_add_f32_e32 v154, 1.0, v154
	v_add_f32_e32 v155, 1.0, v155
	v_add_f32_e32 v156, 1.0, v156
	v_add_f32_e32 v157, 1.0, v157
	v_rcp_f32_e32 v154, v154
	v_rcp_f32_e32 v155, v155
	v_rcp_f32_e32 v156, v156
	v_rcp_f32_e32 v157, v157
	v_lshlrev_b32_e32 v150, 16, v178
	v_and_b32_e32 v151, 0xffff0000, v178
	v_lshlrev_b32_e32 v152, 16, v179
	v_and_b32_e32 v153, 0xffff0000, v179
	v_pk_fma_f32 v[14:15], v[154:155], v[150:151], v[146:147]
	v_pk_fma_f32 v[16:17], v[156:157], v[152:153], v[148:149]
	v_pk_mul_f32 v[194:195], v[14:15], v[14:15]
	v_pk_mul_f32 v[196:197], v[16:17], v[16:17]
	v_cvt_f32_i32_e32 v10, v10
	v_cvt_f32_i32_e32 v11, v11
	v_cvt_f32_i32_e32 v12, v12
	v_cvt_f32_i32_e32 v13, v13
	v_pk_mul_f32 v[142:143], v[226:227], v[188:189] op_sel_hi:[1,0]
	v_pk_mul_f32 v[144:145], v[228:229], v[188:189] op_sel_hi:[1,0]
	v_pk_fma_f32 v[154:155], v[142:143], v[10:11], v[210:211]
	v_pk_fma_f32 v[156:157], v[144:145], v[12:13], v[212:213]
	v_mul_f32_e32 v154, 0xbfb8aa3b, v154
	v_mul_f32_e32 v155, 0xbfb8aa3b, v155
	v_mul_f32_e32 v156, 0xbfb8aa3b, v156
	v_mul_f32_e32 v157, 0xbfb8aa3b, v157
	v_exp_f32_e32 v154, v154
	v_exp_f32_e32 v155, v155
	v_exp_f32_e32 v156, v156
	v_exp_f32_e32 v157, v157
	v_lshlrev_b32_e32 v146, 16, v172
	v_and_b32_e32 v147, 0xffff0000, v172
	v_lshlrev_b32_e32 v148, 16, v173
	v_and_b32_e32 v149, 0xffff0000, v173
	v_add_f32_e32 v154, 1.0, v154
	v_add_f32_e32 v155, 1.0, v155
	v_add_f32_e32 v156, 1.0, v156
	v_add_f32_e32 v157, 1.0, v157
	v_rcp_f32_e32 v154, v154
	v_rcp_f32_e32 v155, v155
	v_rcp_f32_e32 v156, v156
	v_rcp_f32_e32 v157, v157
	v_lshlrev_b32_e32 v150, 16, v180
	v_and_b32_e32 v151, 0xffff0000, v180
	v_lshlrev_b32_e32 v152, 16, v181
	v_and_b32_e32 v153, 0xffff0000, v181
	v_pk_fma_f32 v[10:11], v[154:155], v[150:151], v[146:147]
	v_pk_fma_f32 v[12:13], v[156:157], v[152:153], v[148:149]
	v_pk_fma_f32 v[194:195], v[10:11], v[10:11], v[194:195]
	v_pk_fma_f32 v[196:197], v[12:13], v[12:13], v[196:197]
	v_cvt_f32_i32_e32 v6, v6
	v_cvt_f32_i32_e32 v7, v7
	v_cvt_f32_i32_e32 v8, v8
	v_cvt_f32_i32_e32 v9, v9
	v_pk_mul_f32 v[142:143], v[230:231], v[188:189] op_sel_hi:[1,0]
	v_pk_mul_f32 v[144:145], v[232:233], v[188:189] op_sel_hi:[1,0]
	v_pk_fma_f32 v[154:155], v[142:143], v[6:7], v[214:215]
	v_pk_fma_f32 v[156:157], v[144:145], v[8:9], v[216:217]
	v_mul_f32_e32 v154, 0xbfb8aa3b, v154
	v_mul_f32_e32 v155, 0xbfb8aa3b, v155
	v_mul_f32_e32 v156, 0xbfb8aa3b, v156
	v_mul_f32_e32 v157, 0xbfb8aa3b, v157
	v_exp_f32_e32 v154, v154
	v_exp_f32_e32 v155, v155
	v_exp_f32_e32 v156, v156
	v_exp_f32_e32 v157, v157
	v_lshlrev_b32_e32 v146, 16, v174
	v_and_b32_e32 v147, 0xffff0000, v174
	v_lshlrev_b32_e32 v148, 16, v175
	v_and_b32_e32 v149, 0xffff0000, v175
	v_add_f32_e32 v154, 1.0, v154
	v_add_f32_e32 v155, 1.0, v155
	v_add_f32_e32 v156, 1.0, v156
	v_add_f32_e32 v157, 1.0, v157
	v_rcp_f32_e32 v154, v154
	v_rcp_f32_e32 v155, v155
	v_rcp_f32_e32 v156, v156
	v_rcp_f32_e32 v157, v157
	v_lshlrev_b32_e32 v150, 16, v182
	v_and_b32_e32 v151, 0xffff0000, v182
	v_lshlrev_b32_e32 v152, 16, v183
	v_and_b32_e32 v153, 0xffff0000, v183
	v_pk_fma_f32 v[6:7], v[154:155], v[150:151], v[146:147]
	v_pk_fma_f32 v[8:9], v[156:157], v[152:153], v[148:149]
	v_pk_fma_f32 v[194:195], v[6:7], v[6:7], v[194:195]
	v_pk_fma_f32 v[196:197], v[8:9], v[8:9], v[196:197]
	v_cvt_f32_i32_e32 v2, v2
	v_cvt_f32_i32_e32 v3, v3
	v_cvt_f32_i32_e32 v4, v4
	v_cvt_f32_i32_e32 v5, v5
	v_pk_mul_f32 v[142:143], v[234:235], v[188:189] op_sel_hi:[1,0]
	v_pk_mul_f32 v[144:145], v[236:237], v[188:189] op_sel_hi:[1,0]
	v_pk_fma_f32 v[154:155], v[142:143], v[2:3], v[218:219]
	v_pk_fma_f32 v[156:157], v[144:145], v[4:5], v[220:221]
	v_mul_f32_e32 v154, 0xbfb8aa3b, v154
	v_mul_f32_e32 v155, 0xbfb8aa3b, v155
	v_mul_f32_e32 v156, 0xbfb8aa3b, v156
	v_mul_f32_e32 v157, 0xbfb8aa3b, v157
	v_exp_f32_e32 v154, v154
	v_exp_f32_e32 v155, v155
	v_exp_f32_e32 v156, v156
	v_exp_f32_e32 v157, v157
	v_lshlrev_b32_e32 v146, 16, v176
	v_and_b32_e32 v147, 0xffff0000, v176
	v_lshlrev_b32_e32 v148, 16, v177
	v_and_b32_e32 v149, 0xffff0000, v177
	v_add_f32_e32 v154, 1.0, v154
	v_add_f32_e32 v155, 1.0, v155
	v_add_f32_e32 v156, 1.0, v156
	v_add_f32_e32 v157, 1.0, v157
	v_rcp_f32_e32 v154, v154
	v_rcp_f32_e32 v155, v155
	v_rcp_f32_e32 v156, v156
	v_rcp_f32_e32 v157, v157
	v_lshlrev_b32_e32 v150, 16, v184
	v_and_b32_e32 v151, 0xffff0000, v184
	v_lshlrev_b32_e32 v152, 16, v185
	v_and_b32_e32 v153, 0xffff0000, v185
	v_pk_fma_f32 v[2:3], v[154:155], v[150:151], v[146:147]
	v_pk_fma_f32 v[4:5], v[156:157], v[152:153], v[148:149]
	v_pk_fma_f32 v[194:195], v[2:3], v[2:3], v[194:195]
	v_pk_fma_f32 v[196:197], v[4:5], v[4:5], v[196:197]
	v_add_f32_e32 v194, v194, v195
	v_add_f32_e32 v196, v196, v197
	v_add_f32_e32 v194, v194, v196
	ds_bpermute_b32 v195, v58, v194
	s_waitcnt lgkmcnt(0)
	v_add_f32_e32 v194, v194, v195
	ds_bpermute_b32 v195, v59, v194
	s_waitcnt lgkmcnt(0)
	v_add_f32_e32 v194, v194, v195
	s_and_saveexec_b64 s[32:33], s[6:7]
	global_atomic_add_f32 v54, v194, s[70:71] offset:704
	s_or_b64 exec, exec, s[32:33]
	s_waitcnt vmcnt(0)
	s_barrier
; template <class Epi, class Sched, bool ALIGN_EPI = false, bool SP2 = false>
; __device__ __forceinline__ void gemm_phase(PG8_LAS unsigned char* lds, const Gemm g, const Sched& S, const Epi& E) {
;     ...
;         if constexpr (!Epi::AFTER_DRAIN) { E(acc, cur, wr, wc, fr, fq); S.done(cur); }
; __global__ void __launch_bounds__(512, 2) k_fwd(Args a_unused) {
;     ...
;     if (IN(9)) { PH_IDS(); ph_final_norm(ap->out, ctl + CW_RSS3, ap->in[21], gt, NGT); }
	s_load_dwordx2 s[100:101], s[92:93], 0xa8
	s_lshl_b32 s48, s98, 7
	s_add_u32 s50, s26, s48
	s_addc_u32 s51, s27, 0
	s_add_u32 s50, s50, 0x10000
	s_addc_u32 s51, s51, 0
	s_and_saveexec_b64 s[52:53], s[96:97]
	s_cbranch_execz .Lfz_poll_done
	v_mov_b32_e32 v60, 0
	v_mov_b32_e32 v61, 1
	global_atomic_add v60, v61, s[50:51]
	s_mov_b32 s49, 0
